# first K-iteration of each GEMM loop peeled, first-touch MFMAs use SrcC=0: no accumulator zeroing at tile start
# speedup vs baseline: 1.0029x; 1.0010x over previous
; #define PG8_STAGEA(bufoff, gbase, voff) PG8_STAGE_X(bufoff, gbase, voff, AUXA)
; #define PG8_STAGEB(bufoff, gbase, voff) PG8_STAGE_X(bufoff, gbase, voff, AUXB)
; #define PG8_LDA(dst, b, h) do { _Pragma("unroll") for (int m = 0; m < 4; ++m) _Pragma("unroll") for (int k = 0; k < 2; ++k) dst[m][k] = *(const PG8_LAS bf16x8*)(lds + PG8_SA(b, h) + aoff + m * 2048 + k * 1024); } while (0)
; #define PG8_LDB(dst, b, h) do { _Pragma("unroll") for (int n = 0; n < 2; ++n) _Pragma("unroll") for (int k = 0; k < 2; ++k) dst[n][k] = *(const PG8_LAS bf16x8*)(lds + PG8_SB(b, h) + boff + n * 2048 + k * 1024); } while (0)
; #define PG8_MMA(ai, bj, At, Bt) do { if (GEMM_PRIO_MODE == 0) __builtin_amdgcn_s_setprio(1); PG8_MMA_LOOPS \
;         acc[ai][bj][m][n] = __builtin_amdgcn_mfma_f32_16x16x32_bf16(Bt[n][k], At[m][k], acc[ai][bj][m][n], 0, 0, 0); if (GEMM_PRIO_MODE == 0) __builtin_amdgcn_s_setprio(0); } while (0)
; #define PG8_WAIT_V(n) asm volatile("s_waitcnt vmcnt(" #n ")" ::: "memory")
; #define PG8_WAIT_L(n) asm volatile("s_waitcnt lgkmcnt(" #n ")" ::: "memory")
;     ...
;         for (int t = t0; t < nt; t += 2) {
;             const bool last = (t == nt - 2);
;             const char* a1 = cA + (size_t)(t + 1) * kstepA;
;             const char* a2 = last ? nA : cA + (size_t)(t + 2) * kstepA; const char* b2 = last ? nB : cB + (size_t)(t + 2) * kstepB;
;             const char* a3 = a2 + kstepA; const char* b3 = b2 + kstepB;
;             if (last && has_next) S.a_ready(nxt);
;             if constexpr (SP2) {
;             PG8_LDB(B0, 0, 0); PG8_LDB(B1, 0, 1); PG8_SCHED; PG8_LDA(At, 0, 0); PG8_STAGEA(PG8_SA(1, 1), a1 + hstepA, voffA);
;     ...
;             const int relax = __builtin_amdgcn_readfirstlane((t == 0 && ui > 0) ? 1 : 0);
;             PG8_WAIT_VR(8, 24, relax); PG8_WAIT_L(0); PG8_BAR; PG8_MMA(0, 0, At, B0); PG8_MMA(0, 1, At, B1); PG8_BAR; PG8_SCHED;
;     ...
;             PG8_WAIT_V(8); PG8_WAIT_L(0); PG8_BAR; PG8_MMA(0, 0, At, B0); PG8_MMA(0, 1, At, B1); PG8_BAR; PG8_SCHED;
;     ...
;             PG8_LDA(At, 0, 1); PG8_STAGEB(PG8_SB(0, 0), b2, voffB); PG8_STAGEB(PG8_SB(0, 1), b2 + hstepB, voffB); PG8_STAGEA(PG8_SA(0, 0), a2, voffA);
;     ...
;             PG8_WAIT_VR(8, 24, relax); PG8_WAIT_L(0); PG8_BAR; PG8_MMA(1, 0, At, B0); PG8_MMA(1, 1, At, B1); PG8_BAR; PG8_SCHED;
;     ...
;             PG8_WAIT_V(8); PG8_WAIT_L(0); PG8_BAR; PG8_MMA(1, 0, At, B0); PG8_MMA(1, 1, At, B1); PG8_BAR; PG8_SCHED;
.LBB0_128:
	s_ashr_i32 s37, s36, 31
	s_lshl_b64 s[4:5], s[36:37], 21
	s_add_u32 s38, s56, s4
	s_addc_u32 s39, s57, s5
	s_and_b64 s[4:5], s[6:7], exec
	s_cselect_b32 s4, s39, s1
	s_cselect_b32 s5, s38, s0
	s_ashr_i32 s27, s26, 31
	s_lshl_b64 s[8:9], s[26:27], 21
	s_add_u32 s40, s43, s8
	s_addc_u32 s41, s50, s9
	s_and_b64 s[8:9], s[6:7], exec
	s_cselect_b32 s16, s41, s11
	s_cselect_b32 s17, s40, s10
	s_add_u32 s8, s0, 0x100080
	s_addc_u32 s9, s1, 0
	s_add_u32 s0, s10, 0x100
	s_addc_u32 s1, s11, 0
	s_mov_b32 s27, -2
	s_add_u32 s10, s8, 0xfff00080
	s_addc_u32 s11, s9, -1
	s_add_i32 s18, 0, 0x10000
	s_cmp_eq_u32 s27, 60
	s_cselect_b32 s15, s4, s11
	s_cselect_b32 s14, s5, s10
	v_add_u32_e32 v16, s18, v167
	s_cselect_b32 s11, s16, s1
	s_cselect_b32 s10, s17, s0
	s_add_i32 s20, 0, 0x14000
	s_waitcnt lgkmcnt(0)
	ds_read_b128 v[130:133], v16
	ds_read_b128 v[134:137], v16 offset:1024
	ds_read_b128 v[152:155], v16 offset:2048
	ds_read_b128 v[156:159], v16 offset:3072
	v_add_u32_e32 v16, s20, v167
	ds_read_b128 v[160:163], v16
	ds_read_b128 v[174:177], v16 offset:1024
	ds_read_b128 v[178:181], v16 offset:2048
	ds_read_b128 v[182:185], v16 offset:3072
	v_lshl_add_u64 v[164:165], s[8:9], 0, v[148:149]
	s_add_i32 m0, s51, 0xc000
	ds_read_b128 v[186:189], v172
	ds_read_b128 v[190:193], v172 offset:1024
	ds_read_b128 v[194:197], v172 offset:2048
	ds_read_b128 v[198:201], v172 offset:3072
	ds_read_b128 v[202:205], v172 offset:4096
	ds_read_b128 v[206:209], v172 offset:5120
	ds_read_b128 v[210:213], v172 offset:6144
	ds_read_b128 v[214:217], v172 offset:7168
	global_load_lds_dwordx4 v[164:165], off
	v_lshl_add_u64 v[164:165], s[8:9], 0, v[150:151]
	s_add_i32 m0, s51, 0xe000
	s_nop 0
	global_load_lds_dwordx4 v[164:165], off
	s_waitcnt vmcnt(8)
	s_waitcnt lgkmcnt(0)
	s_setprio 1
	s_barrier
	v_mfma_f32_16x16x32_bf16 v[126:129], v[130:133], v[186:189], 0
	v_mfma_f32_16x16x32_bf16 v[122:125], v[152:155], v[186:189], 0
	v_mfma_f32_16x16x32_bf16 v[110:113], v[130:133], v[194:197], 0
	v_mfma_f32_16x16x32_bf16 v[106:109], v[152:155], v[194:197], 0
	v_mfma_f32_16x16x32_bf16 v[94:97], v[130:133], v[202:205], 0
	v_mfma_f32_16x16x32_bf16 v[90:93], v[152:155], v[202:205], 0
	v_mfma_f32_16x16x32_bf16 v[78:81], v[130:133], v[210:213], 0
	v_mfma_f32_16x16x32_bf16 v[74:77], v[152:155], v[210:213], 0
	v_mfma_f32_16x16x32_bf16 v[126:129], v[134:137], v[190:193], v[126:129]
	v_mfma_f32_16x16x32_bf16 v[122:125], v[156:159], v[190:193], v[122:125]
	v_mfma_f32_16x16x32_bf16 v[110:113], v[134:137], v[198:201], v[110:113]
	v_mfma_f32_16x16x32_bf16 v[106:109], v[156:159], v[198:201], v[106:109]
	v_mfma_f32_16x16x32_bf16 v[94:97], v[134:137], v[206:209], v[94:97]
	v_mfma_f32_16x16x32_bf16 v[90:93], v[156:159], v[206:209], v[90:93]
	v_mfma_f32_16x16x32_bf16 v[78:81], v[134:137], v[214:217], v[78:81]
	v_mfma_f32_16x16x32_bf16 v[74:77], v[156:159], v[214:217], v[74:77]
	v_mfma_f32_16x16x32_bf16 v[118:121], v[160:163], v[186:189], 0
	v_mfma_f32_16x16x32_bf16 v[114:117], v[178:181], v[186:189], 0
	v_mfma_f32_16x16x32_bf16 v[102:105], v[160:163], v[194:197], 0
	v_mfma_f32_16x16x32_bf16 v[98:101], v[178:181], v[194:197], 0
	v_mfma_f32_16x16x32_bf16 v[86:89], v[160:163], v[202:205], 0
	v_mfma_f32_16x16x32_bf16 v[82:85], v[178:181], v[202:205], 0
	v_mfma_f32_16x16x32_bf16 v[70:73], v[160:163], v[210:213], 0
	v_mfma_f32_16x16x32_bf16 v[66:69], v[178:181], v[210:213], 0
	v_mfma_f32_16x16x32_bf16 v[118:121], v[174:177], v[190:193], v[118:121]
	v_mfma_f32_16x16x32_bf16 v[114:117], v[182:185], v[190:193], v[114:117]
	v_mfma_f32_16x16x32_bf16 v[102:105], v[174:177], v[198:201], v[102:105]
	v_mfma_f32_16x16x32_bf16 v[98:101], v[182:185], v[198:201], v[98:101]
	v_mfma_f32_16x16x32_bf16 v[86:89], v[174:177], v[206:209], v[86:89]
	v_mfma_f32_16x16x32_bf16 v[82:85], v[182:185], v[206:209], v[82:85]
	v_mfma_f32_16x16x32_bf16 v[70:73], v[174:177], v[214:217], v[70:73]
	v_mfma_f32_16x16x32_bf16 v[66:69], v[182:185], v[214:217], v[66:69]
	s_barrier
	s_setprio 0
	s_add_i32 s18, s18, s42
	v_lshl_add_u64 v[164:165], s[10:11], 0, v[142:143]
	s_mov_b32 m0, s18
	ds_read_b128 v[186:189], v172 offset:16384
	ds_read_b128 v[190:193], v172 offset:17408
	ds_read_b128 v[194:197], v172 offset:18432
	ds_read_b128 v[198:201], v172 offset:19456
	ds_read_b128 v[202:205], v172 offset:20480
	ds_read_b128 v[206:209], v172 offset:21504
	ds_read_b128 v[210:213], v172 offset:22528
	ds_read_b128 v[214:217], v172 offset:23552
	global_load_lds_dwordx4 v[164:165], off
	s_add_i32 m0, s18, 0x2000
	s_add_u32 s18, s10, 0x100000
	v_lshl_add_u64 v[218:219], s[10:11], 0, v[138:139]
	s_addc_u32 s19, s11, 0
	s_add_i32 s20, s20, s42
	global_load_lds_dwordx4 v[218:219], off
	v_lshl_add_u64 v[220:221], s[18:19], 0, v[142:143]
	s_mov_b32 m0, s20
	v_lshl_add_u64 v[222:223], s[14:15], 0, v[140:141]
	global_load_lds_dwordx4 v[220:221], off
	v_lshl_add_u64 v[220:221], s[18:19], 0, v[138:139]
	s_add_i32 m0, s20, 0x2000
	s_nop 0
	global_load_lds_dwordx4 v[220:221], off
	v_lshl_add_u64 v[220:221], s[14:15], 0, v[144:145]
	s_mov_b32 m0, s51
	s_nop 0
	global_load_lds_dwordx4 v[220:221], off
	s_mov_b32 m0, s68
	s_nop 0
	global_load_lds_dwordx4 v[222:223], off
	s_waitcnt vmcnt(8)
	s_waitcnt lgkmcnt(0)
	s_setprio 1
	s_barrier
; #define PG8_STAGEA(bufoff, gbase, voff) PG8_STAGE_X(bufoff, gbase, voff, AUXA)
; #define PG8_STAGEB(bufoff, gbase, voff) PG8_STAGE_X(bufoff, gbase, voff, AUXB)
; #define PG8_LDA(dst, b, h) do { _Pragma("unroll") for (int m = 0; m < 4; ++m) _Pragma("unroll") for (int k = 0; k < 2; ++k) dst[m][k] = *(const PG8_LAS bf16x8*)(lds + PG8_SA(b, h) + aoff + m * 2048 + k * 1024); } while (0)
; #define PG8_LDB(dst, b, h) do { _Pragma("unroll") for (int n = 0; n < 2; ++n) _Pragma("unroll") for (int k = 0; k < 2; ++k) dst[n][k] = *(const PG8_LAS bf16x8*)(lds + PG8_SB(b, h) + boff + n * 2048 + k * 1024); } while (0)
; #define PG8_MMA(ai, bj, At, Bt) do { if (GEMM_PRIO_MODE == 0) __builtin_amdgcn_s_setprio(1); PG8_MMA_LOOPS \
;         acc[ai][bj][m][n] = __builtin_amdgcn_mfma_f32_16x16x32_bf16(Bt[n][k], At[m][k], acc[ai][bj][m][n], 0, 0, 0); if (GEMM_PRIO_MODE == 0) __builtin_amdgcn_s_setprio(0); } while (0)
; #define PG8_WAIT_V(n) asm volatile("s_waitcnt vmcnt(" #n ")" ::: "memory")
; #define PG8_WAIT_VR(n, nr, flag) asm volatile("s_cmp_eq_u32 %0, 0\n\ts_cbranch_scc1 .Lpg8s%=\n\ts_waitcnt vmcnt(" #nr ")\n\ts_branch .Lpg8d%=\n.Lpg8s%=:\n\ts_waitcnt vmcnt(" #n ")\n.Lpg8d%=:" :: "s"(flag) : "memory", "scc")
; #define PG8_WAIT_L(n) asm volatile("s_waitcnt lgkmcnt(" #n ")" ::: "memory")
; #define PG8_BAR __builtin_amdgcn_s_barrier()
; #define PG8_SCHED __builtin_amdgcn_sched_barrier(0)
;     ...
;             PG8_LDA(At, 0, 1); PG8_STAGEB(PG8_SB(0, 0), b2, voffB); PG8_STAGEB(PG8_SB(0, 1), b2 + hstepB, voffB); PG8_STAGEA(PG8_SA(0, 0), a2, voffA);
;     ...
;             PG8_WAIT_VR(8, 24, relax); PG8_WAIT_L(0); PG8_BAR; PG8_MMA(1, 0, At, B0); PG8_MMA(1, 1, At, B1); PG8_BAR; PG8_SCHED;
;     ...
;             PG8_WAIT_V(8); PG8_WAIT_L(0); PG8_BAR; PG8_MMA(1, 0, At, B0); PG8_MMA(1, 1, At, B1); PG8_BAR; PG8_SCHED;
;     ...
;             PG8_LDB(B0, 1, 0); PG8_LDB(B1, 1, 1); PG8_SCHED; PG8_LDA(At, 1, 0); PG8_STAGEA(PG8_SA(0, 1), a2 + hstepA, voffA);
;             PG8_WAIT_V(8); PG8_WAIT_L(0); PG8_BAR; PG8_MMA(0, 0, At, B0); PG8_MMA(0, 1, At, B1); PG8_BAR; PG8_SCHED;
	v_mfma_f32_16x16x32_bf16 v[62:65], v[130:133], v[186:189], 0
	v_mfma_f32_16x16x32_bf16 v[58:61], v[152:155], v[186:189], 0
	v_mfma_f32_16x16x32_bf16 v[46:49], v[130:133], v[194:197], 0
	v_mfma_f32_16x16x32_bf16 v[42:45], v[152:155], v[194:197], 0
	v_mfma_f32_16x16x32_bf16 v[30:33], v[130:133], v[202:205], 0
	v_mfma_f32_16x16x32_bf16 v[26:29], v[152:155], v[202:205], 0
	v_mfma_f32_16x16x32_bf16 v[12:15], v[130:133], v[210:213], 0
	v_mfma_f32_16x16x32_bf16 v[8:11], v[152:155], v[210:213], 0
	v_mfma_f32_16x16x32_bf16 v[62:65], v[134:137], v[190:193], v[62:65]
	v_mfma_f32_16x16x32_bf16 v[58:61], v[156:159], v[190:193], v[58:61]
	v_mfma_f32_16x16x32_bf16 v[46:49], v[134:137], v[198:201], v[46:49]
	v_mfma_f32_16x16x32_bf16 v[42:45], v[156:159], v[198:201], v[42:45]
	v_mfma_f32_16x16x32_bf16 v[30:33], v[134:137], v[206:209], v[30:33]
	v_mfma_f32_16x16x32_bf16 v[26:29], v[156:159], v[206:209], v[26:29]
	v_mfma_f32_16x16x32_bf16 v[12:15], v[134:137], v[214:217], v[12:15]
	v_mfma_f32_16x16x32_bf16 v[8:11], v[156:159], v[214:217], v[8:11]
	v_mfma_f32_16x16x32_bf16 v[54:57], v[160:163], v[186:189], 0
	v_mfma_f32_16x16x32_bf16 v[50:53], v[178:181], v[186:189], 0
	v_mfma_f32_16x16x32_bf16 v[38:41], v[160:163], v[194:197], 0
	v_mfma_f32_16x16x32_bf16 v[34:37], v[178:181], v[194:197], 0
	v_mfma_f32_16x16x32_bf16 v[22:25], v[160:163], v[202:205], 0
	v_mfma_f32_16x16x32_bf16 v[18:21], v[178:181], v[202:205], 0
	v_mfma_f32_16x16x32_bf16 v[4:7], v[160:163], v[210:213], 0
	v_mfma_f32_16x16x32_bf16 v[0:3], v[178:181], v[210:213], 0
	v_mfma_f32_16x16x32_bf16 v[54:57], v[174:177], v[190:193], v[54:57]
	v_mfma_f32_16x16x32_bf16 v[50:53], v[182:185], v[190:193], v[50:53]
	v_mfma_f32_16x16x32_bf16 v[38:41], v[174:177], v[198:201], v[38:41]
	v_mfma_f32_16x16x32_bf16 v[34:37], v[182:185], v[198:201], v[34:37]
	v_mfma_f32_16x16x32_bf16 v[22:25], v[174:177], v[206:209], v[22:25]
	v_mfma_f32_16x16x32_bf16 v[18:21], v[182:185], v[206:209], v[18:21]
	v_mfma_f32_16x16x32_bf16 v[4:7], v[174:177], v[214:217], v[4:7]
	v_mfma_f32_16x16x32_bf16 v[0:3], v[182:185], v[214:217], v[0:3]
	s_barrier
	s_setprio 0
	s_add_i32 s18, 0, 0x18000
	v_add_u32_e32 v16, s18, v167
	s_add_i32 s19, 0, 0x1c000
	ds_read_b128 v[130:133], v16
	ds_read_b128 v[134:137], v16 offset:1024
	ds_read_b128 v[152:155], v16 offset:2048
	ds_read_b128 v[156:159], v16 offset:3072
	v_add_u32_e32 v16, s19, v167
	ds_read_b128 v[160:163], v16
	ds_read_b128 v[174:177], v16 offset:1024
	ds_read_b128 v[178:181], v16 offset:2048
	ds_read_b128 v[182:185], v16 offset:3072
	s_add_u32 s14, s14, 0x100000
	s_addc_u32 s15, s15, 0
	s_mov_b32 m0, s69
	v_lshl_add_u64 v[224:225], s[14:15], 0, v[144:145]
	ds_read_b128 v[186:189], v172 offset:32768
	ds_read_b128 v[190:193], v172 offset:33792
	ds_read_b128 v[194:197], v172 offset:34816
	ds_read_b128 v[198:201], v172 offset:35840
	ds_read_b128 v[202:205], v172 offset:36864
	ds_read_b128 v[206:209], v172 offset:37888
	ds_read_b128 v[210:213], v172 offset:38912
	ds_read_b128 v[214:217], v172 offset:39936
	global_load_lds_dwordx4 v[224:225], off
	v_lshl_add_u64 v[224:225], s[14:15], 0, v[140:141]
	s_mov_b32 m0, s72
	s_nop 0
	global_load_lds_dwordx4 v[224:225], off
	s_waitcnt vmcnt(8)
	s_waitcnt lgkmcnt(0)
	s_setprio 1
	s_barrier
	v_mfma_f32_16x16x32_bf16 v[126:129], v[130:133], v[186:189], v[126:129]
	v_mfma_f32_16x16x32_bf16 v[122:125], v[152:155], v[186:189], v[122:125]
	v_mfma_f32_16x16x32_bf16 v[110:113], v[130:133], v[194:197], v[110:113]
	v_mfma_f32_16x16x32_bf16 v[106:109], v[152:155], v[194:197], v[106:109]
	v_mfma_f32_16x16x32_bf16 v[94:97], v[130:133], v[202:205], v[94:97]
	v_mfma_f32_16x16x32_bf16 v[90:93], v[152:155], v[202:205], v[90:93]
	v_mfma_f32_16x16x32_bf16 v[78:81], v[130:133], v[210:213], v[78:81]
	v_mfma_f32_16x16x32_bf16 v[74:77], v[152:155], v[210:213], v[74:77]
	v_mfma_f32_16x16x32_bf16 v[126:129], v[134:137], v[190:193], v[126:129]
	v_mfma_f32_16x16x32_bf16 v[122:125], v[156:159], v[190:193], v[122:125]
	v_mfma_f32_16x16x32_bf16 v[110:113], v[134:137], v[198:201], v[110:113]
	v_mfma_f32_16x16x32_bf16 v[106:109], v[156:159], v[198:201], v[106:109]
	v_mfma_f32_16x16x32_bf16 v[94:97], v[134:137], v[206:209], v[94:97]
	v_mfma_f32_16x16x32_bf16 v[90:93], v[156:159], v[206:209], v[90:93]
	v_mfma_f32_16x16x32_bf16 v[78:81], v[134:137], v[214:217], v[78:81]
	v_mfma_f32_16x16x32_bf16 v[74:77], v[156:159], v[214:217], v[74:77]
	v_mfma_f32_16x16x32_bf16 v[118:121], v[160:163], v[186:189], v[118:121]
	v_mfma_f32_16x16x32_bf16 v[114:117], v[178:181], v[186:189], v[114:117]
	v_mfma_f32_16x16x32_bf16 v[102:105], v[160:163], v[194:197], v[102:105]
	v_mfma_f32_16x16x32_bf16 v[98:101], v[178:181], v[194:197], v[98:101]
	v_mfma_f32_16x16x32_bf16 v[86:89], v[160:163], v[202:205], v[86:89]
	v_mfma_f32_16x16x32_bf16 v[82:85], v[178:181], v[202:205], v[82:85]
	v_mfma_f32_16x16x32_bf16 v[70:73], v[160:163], v[210:213], v[70:73]
	v_mfma_f32_16x16x32_bf16 v[66:69], v[178:181], v[210:213], v[66:69]
	v_mfma_f32_16x16x32_bf16 v[118:121], v[174:177], v[190:193], v[118:121]
	v_mfma_f32_16x16x32_bf16 v[114:117], v[182:185], v[190:193], v[114:117]
	v_mfma_f32_16x16x32_bf16 v[102:105], v[174:177], v[198:201], v[102:105]
	v_mfma_f32_16x16x32_bf16 v[98:101], v[182:185], v[198:201], v[98:101]
	v_mfma_f32_16x16x32_bf16 v[86:89], v[174:177], v[206:209], v[86:89]
	v_mfma_f32_16x16x32_bf16 v[82:85], v[182:185], v[206:209], v[82:85]
	v_mfma_f32_16x16x32_bf16 v[70:73], v[174:177], v[214:217], v[70:73]
	v_mfma_f32_16x16x32_bf16 v[66:69], v[182:185], v[214:217], v[66:69]
	s_barrier
; #define PG8_STAGEA(bufoff, gbase, voff) PG8_STAGE_X(bufoff, gbase, voff, AUXA)
; #define PG8_STAGEB(bufoff, gbase, voff) PG8_STAGE_X(bufoff, gbase, voff, AUXB)
; #define PG8_LDA(dst, b, h) do { _Pragma("unroll") for (int m = 0; m < 4; ++m) _Pragma("unroll") for (int k = 0; k < 2; ++k) dst[m][k] = *(const PG8_LAS bf16x8*)(lds + PG8_SA(b, h) + aoff + m * 2048 + k * 1024); } while (0)
; #define PG8_LDB(dst, b, h) do { _Pragma("unroll") for (int n = 0; n < 2; ++n) _Pragma("unroll") for (int k = 0; k < 2; ++k) dst[n][k] = *(const PG8_LAS bf16x8*)(lds + PG8_SB(b, h) + boff + n * 2048 + k * 1024); } while (0)
; #define PG8_MMA(ai, bj, At, Bt) do { if (GEMM_PRIO_MODE == 0) __builtin_amdgcn_s_setprio(1); PG8_MMA_LOOPS \
;         acc[ai][bj][m][n] = __builtin_amdgcn_mfma_f32_16x16x32_bf16(Bt[n][k], At[m][k], acc[ai][bj][m][n], 0, 0, 0); if (GEMM_PRIO_MODE == 0) __builtin_amdgcn_s_setprio(0); } while (0)
; #define PG8_WAIT_V(n) asm volatile("s_waitcnt vmcnt(" #n ")" ::: "memory")
; #define PG8_WAIT_L(n) asm volatile("s_waitcnt lgkmcnt(" #n ")" ::: "memory")
; #define PG8_BAR __builtin_amdgcn_s_barrier()
; #define PG8_SCHED __builtin_amdgcn_sched_barrier(0)
;     ...
;         for (int t = t0; t < nt; t += 2) {
;             const bool last = (t == nt - 2);
;             const char* a1 = cA + (size_t)(t + 1) * kstepA;
;             const char* a2 = last ? nA : cA + (size_t)(t + 2) * kstepA; const char* b2 = last ? nB : cB + (size_t)(t + 2) * kstepB;
;             const char* a3 = a2 + kstepA; const char* b3 = b2 + kstepB;
;     ...
;             PG8_LDB(B0, 1, 0); PG8_LDB(B1, 1, 1); PG8_SCHED; PG8_LDA(At, 1, 0); PG8_STAGEA(PG8_SA(0, 1), a2 + hstepA, voffA);
;             PG8_WAIT_V(8); PG8_WAIT_L(0); PG8_BAR; PG8_MMA(0, 0, At, B0); PG8_MMA(0, 1, At, B1); PG8_BAR; PG8_SCHED;
;             PG8_LDA(At, 1, 1); PG8_STAGEB(PG8_SB(1, 0), b3, voffB); PG8_STAGEB(PG8_SB(1, 1), b3 + hstepB, voffB); PG8_STAGEA(PG8_SA(1, 0), a3, voffA);
;             PG8_WAIT_V(8); PG8_WAIT_L(0); PG8_BAR; PG8_MMA(1, 0, At, B0); PG8_MMA(1, 1, At, B1); PG8_BAR; PG8_SCHED;
	s_setprio 0
	s_add_i32 s14, s18, s42
	v_lshl_add_u64 v[164:165], v[164:165], 0, s[86:87]
	s_mov_b32 m0, s14
	ds_read_b128 v[186:189], v172 offset:49152
	ds_read_b128 v[190:193], v172 offset:50176
	ds_read_b128 v[194:197], v172 offset:51200
	ds_read_b128 v[198:201], v172 offset:52224
	ds_read_b128 v[202:205], v172 offset:53248
	ds_read_b128 v[206:209], v172 offset:54272
	ds_read_b128 v[210:213], v172 offset:55296
	ds_read_b128 v[214:217], v172 offset:56320
	global_load_lds_dwordx4 v[164:165], off
	s_add_i32 m0, s14, 0x2000
	s_add_u32 s10, s10, 0x100080
	v_lshl_add_u64 v[164:165], v[218:219], 0, s[86:87]
	s_addc_u32 s11, s11, 0
	s_add_i32 s14, s19, s42
	global_load_lds_dwordx4 v[164:165], off
	v_lshl_add_u64 v[164:165], s[10:11], 0, v[142:143]
	s_mov_b32 m0, s14
	s_nop 0
	global_load_lds_dwordx4 v[164:165], off
	v_lshl_add_u64 v[164:165], s[10:11], 0, v[138:139]
	s_add_i32 m0, s14, 0x2000
	s_nop 0
	global_load_lds_dwordx4 v[164:165], off
	v_lshl_add_u64 v[164:165], v[220:221], 0, s[86:87]
	s_mov_b32 m0, s73
	s_nop 0
	global_load_lds_dwordx4 v[164:165], off
	v_lshl_add_u64 v[164:165], v[222:223], 0, s[86:87]
	s_mov_b32 m0, s82
	s_nop 0
	global_load_lds_dwordx4 v[164:165], off
	s_waitcnt vmcnt(8)
	s_waitcnt lgkmcnt(0)
	s_setprio 1
	s_barrier
	v_mfma_f32_16x16x32_bf16 v[62:65], v[130:133], v[186:189], v[62:65]
	v_mfma_f32_16x16x32_bf16 v[58:61], v[152:155], v[186:189], v[58:61]
	v_mfma_f32_16x16x32_bf16 v[46:49], v[130:133], v[194:197], v[46:49]
	v_mfma_f32_16x16x32_bf16 v[42:45], v[152:155], v[194:197], v[42:45]
	v_mfma_f32_16x16x32_bf16 v[30:33], v[130:133], v[202:205], v[30:33]
	v_mfma_f32_16x16x32_bf16 v[26:29], v[152:155], v[202:205], v[26:29]
	v_mfma_f32_16x16x32_bf16 v[12:15], v[130:133], v[210:213], v[12:15]
	v_mfma_f32_16x16x32_bf16 v[8:11], v[152:155], v[210:213], v[8:11]
	v_mfma_f32_16x16x32_bf16 v[62:65], v[134:137], v[190:193], v[62:65]
	v_mfma_f32_16x16x32_bf16 v[58:61], v[156:159], v[190:193], v[58:61]
	v_mfma_f32_16x16x32_bf16 v[46:49], v[134:137], v[198:201], v[46:49]
	v_mfma_f32_16x16x32_bf16 v[42:45], v[156:159], v[198:201], v[42:45]
	v_mfma_f32_16x16x32_bf16 v[30:33], v[134:137], v[206:209], v[30:33]
	v_mfma_f32_16x16x32_bf16 v[26:29], v[156:159], v[206:209], v[26:29]
	v_mfma_f32_16x16x32_bf16 v[12:15], v[134:137], v[214:217], v[12:15]
	v_mfma_f32_16x16x32_bf16 v[8:11], v[156:159], v[214:217], v[8:11]
	v_mfma_f32_16x16x32_bf16 v[54:57], v[160:163], v[186:189], v[54:57]
	v_mfma_f32_16x16x32_bf16 v[50:53], v[178:181], v[186:189], v[50:53]
	v_mfma_f32_16x16x32_bf16 v[38:41], v[160:163], v[194:197], v[38:41]
	v_mfma_f32_16x16x32_bf16 v[34:37], v[178:181], v[194:197], v[34:37]
	v_mfma_f32_16x16x32_bf16 v[22:25], v[160:163], v[202:205], v[22:25]
	v_mfma_f32_16x16x32_bf16 v[18:21], v[178:181], v[202:205], v[18:21]
	v_mfma_f32_16x16x32_bf16 v[4:7], v[160:163], v[210:213], v[4:7]
	v_mfma_f32_16x16x32_bf16 v[0:3], v[178:181], v[210:213], v[0:3]
	v_mfma_f32_16x16x32_bf16 v[54:57], v[174:177], v[190:193], v[54:57]
	v_mfma_f32_16x16x32_bf16 v[50:53], v[182:185], v[190:193], v[50:53]
	v_mfma_f32_16x16x32_bf16 v[38:41], v[174:177], v[198:201], v[38:41]
	v_mfma_f32_16x16x32_bf16 v[34:37], v[182:185], v[198:201], v[34:37]
	v_mfma_f32_16x16x32_bf16 v[22:25], v[174:177], v[206:209], v[22:25]
	v_mfma_f32_16x16x32_bf16 v[18:21], v[182:185], v[206:209], v[18:21]
	v_mfma_f32_16x16x32_bf16 v[4:7], v[174:177], v[214:217], v[4:7]
	v_mfma_f32_16x16x32_bf16 v[0:3], v[182:185], v[214:217], v[0:3]
	s_barrier
	s_setprio 0
	s_add_i32 s27, s27, 2
	s_add_u32 s8, s8, 0x100
	s_addc_u32 s9, s9, 0
	s_add_u32 s0, s0, 0x100
	s_addc_u32 s1, s1, 0

; #define PG8_STAGEA(bufoff, gbase, voff) PG8_STAGE_X(bufoff, gbase, voff, AUXA)
; #define PG8_STAGEB(bufoff, gbase, voff) PG8_STAGE_X(bufoff, gbase, voff, AUXB)
; #define PG8_LDA(dst, b, h) do { _Pragma("unroll") for (int m = 0; m < 4; ++m) _Pragma("unroll") for (int k = 0; k < 2; ++k) dst[m][k] = *(const PG8_LAS bf16x8*)(lds + PG8_SA(b, h) + aoff + m * 2048 + k * 1024); } while (0)
; #define PG8_LDB(dst, b, h) do { _Pragma("unroll") for (int n = 0; n < 2; ++n) _Pragma("unroll") for (int k = 0; k < 2; ++k) dst[n][k] = *(const PG8_LAS bf16x8*)(lds + PG8_SB(b, h) + boff + n * 2048 + k * 1024); } while (0)
; #define PG8_MMA(ai, bj, At, Bt) do { if (GEMM_PRIO_MODE == 0) __builtin_amdgcn_s_setprio(1); PG8_MMA_LOOPS \
;         acc[ai][bj][m][n] = __builtin_amdgcn_mfma_f32_16x16x32_bf16(Bt[n][k], At[m][k], acc[ai][bj][m][n], 0, 0, 0); if (GEMM_PRIO_MODE == 0) __builtin_amdgcn_s_setprio(0); } while (0)
; #define PG8_WAIT_V(n) asm volatile("s_waitcnt vmcnt(" #n ")" ::: "memory")
; #define PG8_WAIT_L(n) asm volatile("s_waitcnt lgkmcnt(" #n ")" ::: "memory")
;     ...
;         for (int t = t0; t < nt; t += 2) {
;             const bool last = (t == nt - 2);
;             const char* a1 = cA + (size_t)(t + 1) * kstepA;
;             const char* a2 = last ? nA : cA + (size_t)(t + 2) * kstepA; const char* b2 = last ? nB : cB + (size_t)(t + 2) * kstepB;
;             const char* a3 = a2 + kstepA; const char* b3 = b2 + kstepB;
;             if (last && has_next) S.a_ready(nxt);
;             if constexpr (SP2) {
;             PG8_LDB(B0, 0, 0); PG8_LDB(B1, 0, 1); PG8_SCHED; PG8_LDA(At, 0, 0); PG8_STAGEA(PG8_SA(1, 1), a1 + hstepA, voffA);
;     ...
;             const int relax = __builtin_amdgcn_readfirstlane((t == 0 && ui > 0) ? 1 : 0);
;             PG8_WAIT_VR(8, 24, relax); PG8_WAIT_L(0); PG8_BAR; PG8_MMA(0, 0, At, B0); PG8_MMA(0, 1, At, B1); PG8_BAR; PG8_SCHED;
;     ...
;             PG8_WAIT_V(8); PG8_WAIT_L(0); PG8_BAR; PG8_MMA(0, 0, At, B0); PG8_MMA(0, 1, At, B1); PG8_BAR; PG8_SCHED;
;     ...
;             PG8_LDA(At, 0, 1); PG8_STAGEB(PG8_SB(0, 0), b2, voffB); PG8_STAGEB(PG8_SB(0, 1), b2 + hstepB, voffB); PG8_STAGEA(PG8_SA(0, 0), a2, voffA);
;     ...
;             PG8_WAIT_VR(8, 24, relax); PG8_WAIT_L(0); PG8_BAR; PG8_MMA(1, 0, At, B0); PG8_MMA(1, 1, At, B1); PG8_BAR; PG8_SCHED;
;     ...
;             PG8_WAIT_V(8); PG8_WAIT_L(0); PG8_BAR; PG8_MMA(1, 0, At, B0); PG8_MMA(1, 1, At, B1); PG8_BAR; PG8_SCHED;
.LBB0_557:
	s_ashr_i32 s21, s20, 31
	s_lshl_b64 s[6:7], s[20:21], 21
	s_add_u32 s24, s60, s6
	s_addc_u32 s25, s61, s7
	s_and_b64 s[6:7], s[26:27], exec
	s_cselect_b32 s21, s25, s1
	s_cselect_b32 s82, s24, s0
	s_ashr_i32 s23, s22, 31
	s_lshl_b64 s[6:7], s[22:23], 21
	s_add_u32 s36, s4, s6
	s_addc_u32 s37, s5, s7
	s_and_b64 s[6:7], s[26:27], exec
	s_cselect_b32 s23, s37, s41
	s_cselect_b32 s83, s36, s40
	s_add_u32 s38, s0, 0x100080
	s_addc_u32 s39, s1, 0
	s_add_u32 s0, s40, 0x100
	s_addc_u32 s1, s41, 0
	s_mov_b32 s90, -2
	s_waitcnt lgkmcnt(0)
	s_waitcnt vmcnt(0)
	s_add_u32 s6, s38, 0xfff00080
	s_addc_u32 s7, s39, -1
	s_add_i32 s91, 0, 0x10000
	s_cmp_eq_u32 s90, 60
	s_cselect_b32 s41, s21, s7
	s_cselect_b32 s40, s82, s6
	s_cselect_b32 s17, s23, s1
	s_cselect_b32 s16, s83, s0
	s_add_i32 s94, 0, 0x14000
	v_add_u32_e32 v152, s91, v157
	v_add_u32_e32 v174, s94, v157
	ds_read_b128 v[130:133], v152
	ds_read_b128 v[134:137], v152 offset:1024
	ds_read_b128 v[148:151], v152 offset:2048
	ds_read_b128 v[152:155], v152 offset:3072
	ds_read_b128 v[162:165], v174
	ds_read_b128 v[166:169], v174 offset:1024
	ds_read_b128 v[170:173], v174 offset:2048
	ds_read_b128 v[174:177], v174 offset:3072
	v_lshl_add_u64 v[210:211], s[38:39], 0, v[144:145]
	s_add_i32 m0, s13, 0xc000
	ds_read_b128 v[178:181], v161
	ds_read_b128 v[182:185], v161 offset:1024
	ds_read_b128 v[186:189], v161 offset:2048
	ds_read_b128 v[190:193], v161 offset:3072
	ds_read_b128 v[194:197], v161 offset:4096
	ds_read_b128 v[198:201], v161 offset:5120
	ds_read_b128 v[202:205], v161 offset:6144
	ds_read_b128 v[206:209], v161 offset:7168
	global_load_lds_dwordx4 v[210:211], off
	v_lshl_add_u64 v[210:211], s[38:39], 0, v[146:147]
	s_add_i32 m0, s13, 0xe000
	s_nop 0
	global_load_lds_dwordx4 v[210:211], off
	s_waitcnt vmcnt(8)
	s_waitcnt lgkmcnt(0)
	s_setprio 1
	s_barrier
	v_mfma_f32_16x16x32_bf16 v[126:129], v[130:133], v[178:181], 0
	v_mfma_f32_16x16x32_bf16 v[122:125], v[148:151], v[178:181], 0
	v_mfma_f32_16x16x32_bf16 v[110:113], v[130:133], v[186:189], 0
	v_mfma_f32_16x16x32_bf16 v[106:109], v[148:151], v[186:189], 0
	v_mfma_f32_16x16x32_bf16 v[94:97], v[130:133], v[194:197], 0
	v_mfma_f32_16x16x32_bf16 v[90:93], v[148:151], v[194:197], 0
	v_mfma_f32_16x16x32_bf16 v[78:81], v[130:133], v[202:205], 0
	v_mfma_f32_16x16x32_bf16 v[74:77], v[148:151], v[202:205], 0
	v_mfma_f32_16x16x32_bf16 v[126:129], v[134:137], v[182:185], v[126:129]
	v_mfma_f32_16x16x32_bf16 v[122:125], v[152:155], v[182:185], v[122:125]
	v_mfma_f32_16x16x32_bf16 v[110:113], v[134:137], v[190:193], v[110:113]
	v_mfma_f32_16x16x32_bf16 v[106:109], v[152:155], v[190:193], v[106:109]
	v_mfma_f32_16x16x32_bf16 v[94:97], v[134:137], v[198:201], v[94:97]
	v_mfma_f32_16x16x32_bf16 v[90:93], v[152:155], v[198:201], v[90:93]
	v_mfma_f32_16x16x32_bf16 v[78:81], v[134:137], v[206:209], v[78:81]
	v_mfma_f32_16x16x32_bf16 v[74:77], v[152:155], v[206:209], v[74:77]
	v_mfma_f32_16x16x32_bf16 v[118:121], v[162:165], v[178:181], 0
	v_mfma_f32_16x16x32_bf16 v[114:117], v[170:173], v[178:181], 0
	v_mfma_f32_16x16x32_bf16 v[102:105], v[162:165], v[186:189], 0
	v_mfma_f32_16x16x32_bf16 v[98:101], v[170:173], v[186:189], 0
	v_mfma_f32_16x16x32_bf16 v[86:89], v[162:165], v[194:197], 0
	v_mfma_f32_16x16x32_bf16 v[82:85], v[170:173], v[194:197], 0
	v_mfma_f32_16x16x32_bf16 v[70:73], v[162:165], v[202:205], 0
	v_mfma_f32_16x16x32_bf16 v[66:69], v[170:173], v[202:205], 0
	v_mfma_f32_16x16x32_bf16 v[118:121], v[166:169], v[182:185], v[118:121]
	v_mfma_f32_16x16x32_bf16 v[114:117], v[174:177], v[182:185], v[114:117]
	v_mfma_f32_16x16x32_bf16 v[102:105], v[166:169], v[190:193], v[102:105]
	v_mfma_f32_16x16x32_bf16 v[98:101], v[174:177], v[190:193], v[98:101]
	v_mfma_f32_16x16x32_bf16 v[86:89], v[166:169], v[198:201], v[86:89]
	v_mfma_f32_16x16x32_bf16 v[82:85], v[174:177], v[198:201], v[82:85]
	v_mfma_f32_16x16x32_bf16 v[70:73], v[166:169], v[206:209], v[70:73]
	v_mfma_f32_16x16x32_bf16 v[66:69], v[174:177], v[206:209], v[66:69]
	s_barrier
	s_setprio 0
	s_add_i32 s6, s91, s12
	v_lshl_add_u64 v[210:211], s[16:17], 0, v[16:17]
	s_mov_b32 m0, s6
	ds_read_b128 v[178:181], v161 offset:16384
	ds_read_b128 v[182:185], v161 offset:17408
	ds_read_b128 v[186:189], v161 offset:18432
	ds_read_b128 v[190:193], v161 offset:19456
	ds_read_b128 v[194:197], v161 offset:20480
	ds_read_b128 v[198:201], v161 offset:21504
	ds_read_b128 v[202:205], v161 offset:22528
	ds_read_b128 v[206:209], v161 offset:23552
	global_load_lds_dwordx4 v[210:211], off
	s_add_i32 m0, s6, 0x2000
	s_add_u32 s6, s16, 0x100000
	v_lshl_add_u64 v[212:213], s[16:17], 0, v[138:139]
	s_addc_u32 s7, s17, 0
	s_add_i32 s91, s94, s12
	global_load_lds_dwordx4 v[212:213], off
	v_lshl_add_u64 v[214:215], s[6:7], 0, v[16:17]
	s_mov_b32 m0, s91
	v_lshl_add_u64 v[216:217], s[40:41], 0, v[140:141]
	global_load_lds_dwordx4 v[214:215], off
	v_lshl_add_u64 v[214:215], s[6:7], 0, v[138:139]
	s_add_i32 m0, s91, 0x2000
	s_nop 0
	global_load_lds_dwordx4 v[214:215], off
	v_lshl_add_u64 v[214:215], s[40:41], 0, v[142:143]
	s_mov_b32 m0, s13
	s_nop 0
	global_load_lds_dwordx4 v[214:215], off
	s_mov_b32 m0, s42
	s_nop 0
	global_load_lds_dwordx4 v[216:217], off
	s_waitcnt vmcnt(8)
	s_waitcnt lgkmcnt(0)
	s_setprio 1
	s_barrier
; #define PG8_STAGEA(bufoff, gbase, voff) PG8_STAGE_X(bufoff, gbase, voff, AUXA)
; #define PG8_STAGEB(bufoff, gbase, voff) PG8_STAGE_X(bufoff, gbase, voff, AUXB)
; #define PG8_LDA(dst, b, h) do { _Pragma("unroll") for (int m = 0; m < 4; ++m) _Pragma("unroll") for (int k = 0; k < 2; ++k) dst[m][k] = *(const PG8_LAS bf16x8*)(lds + PG8_SA(b, h) + aoff + m * 2048 + k * 1024); } while (0)
; #define PG8_LDB(dst, b, h) do { _Pragma("unroll") for (int n = 0; n < 2; ++n) _Pragma("unroll") for (int k = 0; k < 2; ++k) dst[n][k] = *(const PG8_LAS bf16x8*)(lds + PG8_SB(b, h) + boff + n * 2048 + k * 1024); } while (0)
; #define PG8_MMA(ai, bj, At, Bt) do { if (GEMM_PRIO_MODE == 0) __builtin_amdgcn_s_setprio(1); PG8_MMA_LOOPS \
;         acc[ai][bj][m][n] = __builtin_amdgcn_mfma_f32_16x16x32_bf16(Bt[n][k], At[m][k], acc[ai][bj][m][n], 0, 0, 0); if (GEMM_PRIO_MODE == 0) __builtin_amdgcn_s_setprio(0); } while (0)
; #define PG8_WAIT_V(n) asm volatile("s_waitcnt vmcnt(" #n ")" ::: "memory")
; #define PG8_WAIT_VR(n, nr, flag) asm volatile("s_cmp_eq_u32 %0, 0\n\ts_cbranch_scc1 .Lpg8s%=\n\ts_waitcnt vmcnt(" #nr ")\n\ts_branch .Lpg8d%=\n.Lpg8s%=:\n\ts_waitcnt vmcnt(" #n ")\n.Lpg8d%=:" :: "s"(flag) : "memory", "scc")
; #define PG8_WAIT_L(n) asm volatile("s_waitcnt lgkmcnt(" #n ")" ::: "memory")
; #define PG8_BAR __builtin_amdgcn_s_barrier()
; #define PG8_SCHED __builtin_amdgcn_sched_barrier(0)
;     ...
;             PG8_LDA(At, 0, 1); PG8_STAGEB(PG8_SB(0, 0), b2, voffB); PG8_STAGEB(PG8_SB(0, 1), b2 + hstepB, voffB); PG8_STAGEA(PG8_SA(0, 0), a2, voffA);
;     ...
;             PG8_WAIT_VR(8, 24, relax); PG8_WAIT_L(0); PG8_BAR; PG8_MMA(1, 0, At, B0); PG8_MMA(1, 1, At, B1); PG8_BAR; PG8_SCHED;
;     ...
;             PG8_WAIT_V(8); PG8_WAIT_L(0); PG8_BAR; PG8_MMA(1, 0, At, B0); PG8_MMA(1, 1, At, B1); PG8_BAR; PG8_SCHED;
;     ...
;             PG8_LDB(B0, 1, 0); PG8_LDB(B1, 1, 1); PG8_SCHED; PG8_LDA(At, 1, 0); PG8_STAGEA(PG8_SA(0, 1), a2 + hstepA, voffA);
;             PG8_WAIT_V(8); PG8_WAIT_L(0); PG8_BAR; PG8_MMA(0, 0, At, B0); PG8_MMA(0, 1, At, B1); PG8_BAR; PG8_SCHED;
	v_mfma_f32_16x16x32_bf16 v[62:65], v[130:133], v[178:181], 0
	v_mfma_f32_16x16x32_bf16 v[58:61], v[148:151], v[178:181], 0
	v_mfma_f32_16x16x32_bf16 v[46:49], v[130:133], v[186:189], 0
	v_mfma_f32_16x16x32_bf16 v[42:45], v[148:151], v[186:189], 0
	v_mfma_f32_16x16x32_bf16 v[30:33], v[130:133], v[194:197], 0
	v_mfma_f32_16x16x32_bf16 v[26:29], v[148:151], v[194:197], 0
	v_mfma_f32_16x16x32_bf16 v[12:15], v[130:133], v[202:205], 0
	v_mfma_f32_16x16x32_bf16 v[8:11], v[148:151], v[202:205], 0
	v_mfma_f32_16x16x32_bf16 v[62:65], v[134:137], v[182:185], v[62:65]
	v_mfma_f32_16x16x32_bf16 v[58:61], v[152:155], v[182:185], v[58:61]
	v_mfma_f32_16x16x32_bf16 v[46:49], v[134:137], v[190:193], v[46:49]
	v_mfma_f32_16x16x32_bf16 v[42:45], v[152:155], v[190:193], v[42:45]
	v_mfma_f32_16x16x32_bf16 v[30:33], v[134:137], v[198:201], v[30:33]
	v_mfma_f32_16x16x32_bf16 v[26:29], v[152:155], v[198:201], v[26:29]
	v_mfma_f32_16x16x32_bf16 v[12:15], v[134:137], v[206:209], v[12:15]
	v_mfma_f32_16x16x32_bf16 v[8:11], v[152:155], v[206:209], v[8:11]
	v_mfma_f32_16x16x32_bf16 v[54:57], v[162:165], v[178:181], 0
	v_mfma_f32_16x16x32_bf16 v[50:53], v[170:173], v[178:181], 0
	v_mfma_f32_16x16x32_bf16 v[38:41], v[162:165], v[186:189], 0
	v_mfma_f32_16x16x32_bf16 v[34:37], v[170:173], v[186:189], 0
	v_mfma_f32_16x16x32_bf16 v[22:25], v[162:165], v[194:197], 0
	v_mfma_f32_16x16x32_bf16 v[18:21], v[170:173], v[194:197], 0
	v_mfma_f32_16x16x32_bf16 v[4:7], v[162:165], v[202:205], 0
	v_mfma_f32_16x16x32_bf16 v[0:3], v[170:173], v[202:205], 0
	v_mfma_f32_16x16x32_bf16 v[54:57], v[166:169], v[182:185], v[54:57]
	v_mfma_f32_16x16x32_bf16 v[50:53], v[174:177], v[182:185], v[50:53]
	v_mfma_f32_16x16x32_bf16 v[38:41], v[166:169], v[190:193], v[38:41]
	v_mfma_f32_16x16x32_bf16 v[34:37], v[174:177], v[190:193], v[34:37]
	v_mfma_f32_16x16x32_bf16 v[22:25], v[166:169], v[198:201], v[22:25]
	v_mfma_f32_16x16x32_bf16 v[18:21], v[174:177], v[198:201], v[18:21]
	v_mfma_f32_16x16x32_bf16 v[4:7], v[166:169], v[206:209], v[4:7]
	v_mfma_f32_16x16x32_bf16 v[0:3], v[174:177], v[206:209], v[0:3]
	s_barrier
	s_setprio 0
	s_add_i32 s91, 0, 0x18000
	s_add_i32 s94, 0, 0x1c000
	v_add_u32_e32 v152, s91, v157
	v_add_u32_e32 v174, s94, v157
	ds_read_b128 v[130:133], v152
	ds_read_b128 v[134:137], v152 offset:1024
	ds_read_b128 v[148:151], v152 offset:2048
	ds_read_b128 v[152:155], v152 offset:3072
	ds_read_b128 v[162:165], v174
	ds_read_b128 v[166:169], v174 offset:1024
	ds_read_b128 v[170:173], v174 offset:2048
	ds_read_b128 v[174:177], v174 offset:3072
	s_add_u32 s6, s40, 0x100000
	s_addc_u32 s7, s41, 0
	s_mov_b32 m0, s43
	v_lshl_add_u64 v[218:219], s[6:7], 0, v[142:143]
	ds_read_b128 v[178:181], v161 offset:32768
	ds_read_b128 v[182:185], v161 offset:33792
	ds_read_b128 v[186:189], v161 offset:34816
	ds_read_b128 v[190:193], v161 offset:35840
	ds_read_b128 v[194:197], v161 offset:36864
	ds_read_b128 v[198:201], v161 offset:37888
	ds_read_b128 v[202:205], v161 offset:38912
	ds_read_b128 v[206:209], v161 offset:39936
	global_load_lds_dwordx4 v[218:219], off
	v_lshl_add_u64 v[218:219], s[6:7], 0, v[140:141]
	s_mov_b32 m0, s50
	s_nop 0
	global_load_lds_dwordx4 v[218:219], off
	s_waitcnt vmcnt(8)
	s_waitcnt lgkmcnt(0)
	s_setprio 1
	s_barrier
	v_mfma_f32_16x16x32_bf16 v[126:129], v[130:133], v[178:181], v[126:129]
	v_mfma_f32_16x16x32_bf16 v[122:125], v[148:151], v[178:181], v[122:125]
	v_mfma_f32_16x16x32_bf16 v[110:113], v[130:133], v[186:189], v[110:113]
	v_mfma_f32_16x16x32_bf16 v[106:109], v[148:151], v[186:189], v[106:109]
	v_mfma_f32_16x16x32_bf16 v[94:97], v[130:133], v[194:197], v[94:97]
	v_mfma_f32_16x16x32_bf16 v[90:93], v[148:151], v[194:197], v[90:93]
	v_mfma_f32_16x16x32_bf16 v[78:81], v[130:133], v[202:205], v[78:81]
	v_mfma_f32_16x16x32_bf16 v[74:77], v[148:151], v[202:205], v[74:77]
	v_mfma_f32_16x16x32_bf16 v[126:129], v[134:137], v[182:185], v[126:129]
	v_mfma_f32_16x16x32_bf16 v[122:125], v[152:155], v[182:185], v[122:125]
	v_mfma_f32_16x16x32_bf16 v[110:113], v[134:137], v[190:193], v[110:113]
	v_mfma_f32_16x16x32_bf16 v[106:109], v[152:155], v[190:193], v[106:109]
	v_mfma_f32_16x16x32_bf16 v[94:97], v[134:137], v[198:201], v[94:97]
	v_mfma_f32_16x16x32_bf16 v[90:93], v[152:155], v[198:201], v[90:93]
	v_mfma_f32_16x16x32_bf16 v[78:81], v[134:137], v[206:209], v[78:81]
	v_mfma_f32_16x16x32_bf16 v[74:77], v[152:155], v[206:209], v[74:77]
	v_mfma_f32_16x16x32_bf16 v[118:121], v[162:165], v[178:181], v[118:121]
	v_mfma_f32_16x16x32_bf16 v[114:117], v[170:173], v[178:181], v[114:117]
	v_mfma_f32_16x16x32_bf16 v[102:105], v[162:165], v[186:189], v[102:105]
	v_mfma_f32_16x16x32_bf16 v[98:101], v[170:173], v[186:189], v[98:101]
	v_mfma_f32_16x16x32_bf16 v[86:89], v[162:165], v[194:197], v[86:89]
	v_mfma_f32_16x16x32_bf16 v[82:85], v[170:173], v[194:197], v[82:85]
	v_mfma_f32_16x16x32_bf16 v[70:73], v[162:165], v[202:205], v[70:73]
	v_mfma_f32_16x16x32_bf16 v[66:69], v[170:173], v[202:205], v[66:69]
	v_mfma_f32_16x16x32_bf16 v[118:121], v[166:169], v[182:185], v[118:121]
	v_mfma_f32_16x16x32_bf16 v[114:117], v[174:177], v[182:185], v[114:117]
	v_mfma_f32_16x16x32_bf16 v[102:105], v[166:169], v[190:193], v[102:105]
	v_mfma_f32_16x16x32_bf16 v[98:101], v[174:177], v[190:193], v[98:101]
	v_mfma_f32_16x16x32_bf16 v[86:89], v[166:169], v[198:201], v[86:89]
	v_mfma_f32_16x16x32_bf16 v[82:85], v[174:177], v[198:201], v[82:85]
	v_mfma_f32_16x16x32_bf16 v[70:73], v[166:169], v[206:209], v[70:73]
	v_mfma_f32_16x16x32_bf16 v[66:69], v[174:177], v[206:209], v[66:69]
	s_barrier
; #define PG8_STAGEA(bufoff, gbase, voff) PG8_STAGE_X(bufoff, gbase, voff, AUXA)
; #define PG8_STAGEB(bufoff, gbase, voff) PG8_STAGE_X(bufoff, gbase, voff, AUXB)
; #define PG8_LDA(dst, b, h) do { _Pragma("unroll") for (int m = 0; m < 4; ++m) _Pragma("unroll") for (int k = 0; k < 2; ++k) dst[m][k] = *(const PG8_LAS bf16x8*)(lds + PG8_SA(b, h) + aoff + m * 2048 + k * 1024); } while (0)
; #define PG8_LDB(dst, b, h) do { _Pragma("unroll") for (int n = 0; n < 2; ++n) _Pragma("unroll") for (int k = 0; k < 2; ++k) dst[n][k] = *(const PG8_LAS bf16x8*)(lds + PG8_SB(b, h) + boff + n * 2048 + k * 1024); } while (0)
; #define PG8_MMA(ai, bj, At, Bt) do { if (GEMM_PRIO_MODE == 0) __builtin_amdgcn_s_setprio(1); PG8_MMA_LOOPS \
;         acc[ai][bj][m][n] = __builtin_amdgcn_mfma_f32_16x16x32_bf16(Bt[n][k], At[m][k], acc[ai][bj][m][n], 0, 0, 0); if (GEMM_PRIO_MODE == 0) __builtin_amdgcn_s_setprio(0); } while (0)
; #define PG8_WAIT_V(n) asm volatile("s_waitcnt vmcnt(" #n ")" ::: "memory")
; #define PG8_WAIT_L(n) asm volatile("s_waitcnt lgkmcnt(" #n ")" ::: "memory")
; #define PG8_BAR __builtin_amdgcn_s_barrier()
; #define PG8_SCHED __builtin_amdgcn_sched_barrier(0)
;     ...
;         for (int t = t0; t < nt; t += 2) {
;             const bool last = (t == nt - 2);
;             const char* a1 = cA + (size_t)(t + 1) * kstepA;
;             const char* a2 = last ? nA : cA + (size_t)(t + 2) * kstepA; const char* b2 = last ? nB : cB + (size_t)(t + 2) * kstepB;
;             const char* a3 = a2 + kstepA; const char* b3 = b2 + kstepB;
;     ...
;             PG8_LDB(B0, 1, 0); PG8_LDB(B1, 1, 1); PG8_SCHED; PG8_LDA(At, 1, 0); PG8_STAGEA(PG8_SA(0, 1), a2 + hstepA, voffA);
;             PG8_WAIT_V(8); PG8_WAIT_L(0); PG8_BAR; PG8_MMA(0, 0, At, B0); PG8_MMA(0, 1, At, B1); PG8_BAR; PG8_SCHED;
;             PG8_LDA(At, 1, 1); PG8_STAGEB(PG8_SB(1, 0), b3, voffB); PG8_STAGEB(PG8_SB(1, 1), b3 + hstepB, voffB); PG8_STAGEA(PG8_SA(1, 0), a3, voffA);
;             PG8_WAIT_V(8); PG8_WAIT_L(0); PG8_BAR; PG8_MMA(1, 0, At, B0); PG8_MMA(1, 1, At, B1); PG8_BAR; PG8_SCHED;
	s_setprio 0
	s_add_i32 s6, s91, s12
	v_lshl_add_u64 v[210:211], v[210:211], 0, s[86:87]
	s_mov_b32 m0, s6
	ds_read_b128 v[178:181], v161 offset:49152
	ds_read_b128 v[182:185], v161 offset:50176
	ds_read_b128 v[186:189], v161 offset:51200
	ds_read_b128 v[190:193], v161 offset:52224
	ds_read_b128 v[194:197], v161 offset:53248
	ds_read_b128 v[198:201], v161 offset:54272
	ds_read_b128 v[202:205], v161 offset:55296
	ds_read_b128 v[206:209], v161 offset:56320
	global_load_lds_dwordx4 v[210:211], off
	s_add_i32 m0, s6, 0x2000
	s_add_u32 s6, s16, 0x100080
	v_lshl_add_u64 v[210:211], v[212:213], 0, s[86:87]
	s_addc_u32 s7, s17, 0
	s_add_i32 s16, s94, s12
	global_load_lds_dwordx4 v[210:211], off
	v_lshl_add_u64 v[210:211], s[6:7], 0, v[16:17]
	s_mov_b32 m0, s16
	s_nop 0
	global_load_lds_dwordx4 v[210:211], off
	v_lshl_add_u64 v[210:211], s[6:7], 0, v[138:139]
	s_add_i32 m0, s16, 0x2000
	s_nop 0
	global_load_lds_dwordx4 v[210:211], off
	v_lshl_add_u64 v[210:211], v[214:215], 0, s[86:87]
	s_mov_b32 m0, s68
	s_nop 0
	global_load_lds_dwordx4 v[210:211], off
	v_lshl_add_u64 v[210:211], v[216:217], 0, s[86:87]
	s_mov_b32 m0, s69
	s_nop 0
	global_load_lds_dwordx4 v[210:211], off
	s_waitcnt vmcnt(8)
	s_waitcnt lgkmcnt(0)
	s_setprio 1
	s_barrier
	v_mfma_f32_16x16x32_bf16 v[62:65], v[130:133], v[178:181], v[62:65]
	v_mfma_f32_16x16x32_bf16 v[58:61], v[148:151], v[178:181], v[58:61]
	v_mfma_f32_16x16x32_bf16 v[46:49], v[130:133], v[186:189], v[46:49]
	v_mfma_f32_16x16x32_bf16 v[42:45], v[148:151], v[186:189], v[42:45]
	v_mfma_f32_16x16x32_bf16 v[30:33], v[130:133], v[194:197], v[30:33]
	v_mfma_f32_16x16x32_bf16 v[26:29], v[148:151], v[194:197], v[26:29]
	v_mfma_f32_16x16x32_bf16 v[12:15], v[130:133], v[202:205], v[12:15]
	v_mfma_f32_16x16x32_bf16 v[8:11], v[148:151], v[202:205], v[8:11]
	v_mfma_f32_16x16x32_bf16 v[62:65], v[134:137], v[182:185], v[62:65]
	v_mfma_f32_16x16x32_bf16 v[58:61], v[152:155], v[182:185], v[58:61]
	v_mfma_f32_16x16x32_bf16 v[46:49], v[134:137], v[190:193], v[46:49]
	v_mfma_f32_16x16x32_bf16 v[42:45], v[152:155], v[190:193], v[42:45]
	v_mfma_f32_16x16x32_bf16 v[30:33], v[134:137], v[198:201], v[30:33]
	v_mfma_f32_16x16x32_bf16 v[26:29], v[152:155], v[198:201], v[26:29]
	v_mfma_f32_16x16x32_bf16 v[12:15], v[134:137], v[206:209], v[12:15]
	v_mfma_f32_16x16x32_bf16 v[8:11], v[152:155], v[206:209], v[8:11]
	v_mfma_f32_16x16x32_bf16 v[54:57], v[162:165], v[178:181], v[54:57]
	v_mfma_f32_16x16x32_bf16 v[50:53], v[170:173], v[178:181], v[50:53]
	v_mfma_f32_16x16x32_bf16 v[38:41], v[162:165], v[186:189], v[38:41]
	v_mfma_f32_16x16x32_bf16 v[34:37], v[170:173], v[186:189], v[34:37]
	v_mfma_f32_16x16x32_bf16 v[22:25], v[162:165], v[194:197], v[22:25]
	v_mfma_f32_16x16x32_bf16 v[18:21], v[170:173], v[194:197], v[18:21]
	v_mfma_f32_16x16x32_bf16 v[4:7], v[162:165], v[202:205], v[4:7]
	v_mfma_f32_16x16x32_bf16 v[0:3], v[170:173], v[202:205], v[0:3]
	v_mfma_f32_16x16x32_bf16 v[54:57], v[166:169], v[182:185], v[54:57]
	v_mfma_f32_16x16x32_bf16 v[50:53], v[174:177], v[182:185], v[50:53]
	v_mfma_f32_16x16x32_bf16 v[38:41], v[166:169], v[190:193], v[38:41]
	v_mfma_f32_16x16x32_bf16 v[34:37], v[174:177], v[190:193], v[34:37]
	v_mfma_f32_16x16x32_bf16 v[22:25], v[166:169], v[198:201], v[22:25]
	v_mfma_f32_16x16x32_bf16 v[18:21], v[174:177], v[198:201], v[18:21]
	v_mfma_f32_16x16x32_bf16 v[4:7], v[166:169], v[206:209], v[4:7]
	v_mfma_f32_16x16x32_bf16 v[0:3], v[174:177], v[206:209], v[0:3]
	s_barrier
	s_setprio 0
	s_add_i32 s90, s90, 2
	s_add_u32 s38, s38, 0x100
	s_addc_u32 s39, s39, 0
	s_add_u32 s0, s0, 0x100
	s_addc_u32 s1, s1, 0

; #define PG8_STAGEA(bufoff, gbase, voff) PG8_STAGE_X(bufoff, gbase, voff, AUXA)
; #define PG8_STAGEB(bufoff, gbase, voff) PG8_STAGE_X(bufoff, gbase, voff, AUXB)
; #define PG8_LDA(dst, b, h) do { _Pragma("unroll") for (int m = 0; m < 4; ++m) _Pragma("unroll") for (int k = 0; k < 2; ++k) dst[m][k] = *(const PG8_LAS bf16x8*)(lds + PG8_SA(b, h) + aoff + m * 2048 + k * 1024); } while (0)
; #define PG8_LDB(dst, b, h) do { _Pragma("unroll") for (int n = 0; n < 2; ++n) _Pragma("unroll") for (int k = 0; k < 2; ++k) dst[n][k] = *(const PG8_LAS bf16x8*)(lds + PG8_SB(b, h) + boff + n * 2048 + k * 1024); } while (0)
; #define PG8_MMA(ai, bj, At, Bt) do { if (GEMM_PRIO_MODE == 0) __builtin_amdgcn_s_setprio(1); PG8_MMA_LOOPS \
;         acc[ai][bj][m][n] = __builtin_amdgcn_mfma_f32_16x16x32_bf16(Bt[n][k], At[m][k], acc[ai][bj][m][n], 0, 0, 0); if (GEMM_PRIO_MODE == 0) __builtin_amdgcn_s_setprio(0); } while (0)
; #define PG8_WAIT_V(n) asm volatile("s_waitcnt vmcnt(" #n ")" ::: "memory")
; #define PG8_WAIT_L(n) asm volatile("s_waitcnt lgkmcnt(" #n ")" ::: "memory")
;     ...
;         for (int t = t0; t < nt; t += 2) {
;             const bool last = (t == nt - 2);
;             const char* a1 = cA + (size_t)(t + 1) * kstepA;
;             const char* a2 = last ? nA : cA + (size_t)(t + 2) * kstepA; const char* b2 = last ? nB : cB + (size_t)(t + 2) * kstepB;
;             const char* a3 = a2 + kstepA; const char* b3 = b2 + kstepB;
;             if (last && has_next) S.a_ready(nxt);
;             if constexpr (SP2) {
;             PG8_LDB(B0, 0, 0); PG8_LDB(B1, 0, 1); PG8_SCHED; PG8_LDA(At, 0, 0); PG8_STAGEA(PG8_SA(1, 1), a1 + hstepA, voffA);
;     ...
;             const int relax = __builtin_amdgcn_readfirstlane((t == 0 && ui > 0) ? 1 : 0);
;             PG8_WAIT_VR(8, 24, relax); PG8_WAIT_L(0); PG8_BAR; PG8_MMA(0, 0, At, B0); PG8_MMA(0, 1, At, B1); PG8_BAR; PG8_SCHED;
;     ...
;             PG8_WAIT_V(8); PG8_WAIT_L(0); PG8_BAR; PG8_MMA(0, 0, At, B0); PG8_MMA(0, 1, At, B1); PG8_BAR; PG8_SCHED;
;     ...
;             PG8_LDA(At, 0, 1); PG8_STAGEB(PG8_SB(0, 0), b2, voffB); PG8_STAGEB(PG8_SB(0, 1), b2 + hstepB, voffB); PG8_STAGEA(PG8_SA(0, 0), a2, voffA);
;     ...
;             PG8_WAIT_VR(8, 24, relax); PG8_WAIT_L(0); PG8_BAR; PG8_MMA(1, 0, At, B0); PG8_MMA(1, 1, At, B1); PG8_BAR; PG8_SCHED;
;     ...
;             PG8_WAIT_V(8); PG8_WAIT_L(0); PG8_BAR; PG8_MMA(1, 0, At, B0); PG8_MMA(1, 1, At, B1); PG8_BAR; PG8_SCHED;
.LBB0_711:
	s_ashr_i32 s25, s24, 31
	s_lshl_b64 s[0:1], s[24:25], 21
	s_add_u32 s26, s56, s0
	s_addc_u32 s27, s57, s1
	s_and_b64 s[0:1], s[10:11], exec
	s_cselect_b32 s0, s27, s13
	s_cselect_b32 s1, s26, s12
	s_ashr_i32 s23, s22, 31
	s_lshl_b64 s[6:7], s[22:23], 21
	s_add_u32 s36, s51, s6
	s_addc_u32 s37, s68, s7
	s_and_b64 s[6:7], s[10:11], exec
	s_cselect_b32 s23, s37, s43
	s_cselect_b32 s25, s36, s42
	s_add_u32 s40, s12, 0x100080
	s_addc_u32 s41, s13, 0
	s_add_u32 s12, s42, 0x100
	s_addc_u32 s13, s43, 0
	s_mov_b32 s39, -2
	s_add_u32 s6, s40, 0xfff00080
	s_addc_u32 s7, s41, -1
	s_add_i32 s95, 0, 0x10000
	s_cmp_eq_u32 s39, 60
	s_cselect_b32 s43, s0, s7
	s_cselect_b32 s42, s1, s6
	v_add_u32_e32 v144, s95, v146
	s_cselect_b32 s17, s23, s13
	s_cselect_b32 s16, s25, s12
	s_add_i32 vcc_lo, 0, 0x14000
	ds_read_b128 v[150:153], v144
	ds_read_b128 v[154:157], v144 offset:1024
	ds_read_b128 v[158:161], v144 offset:2048
	ds_read_b128 v[162:165], v144 offset:3072
	v_add_u32_e32 v144, vcc_lo, v146
	ds_read_b128 v[166:169], v144
	ds_read_b128 v[170:173], v144 offset:1024
	ds_read_b128 v[174:177], v144 offset:2048
	ds_read_b128 v[178:181], v144 offset:3072
	v_lshl_add_u64 v[144:145], s[40:41], 0, v[140:141]
	s_add_i32 m0, s69, 0xc000
	ds_read_b128 v[182:185], v148
	ds_read_b128 v[186:189], v148 offset:1024
	ds_read_b128 v[190:193], v148 offset:2048
	ds_read_b128 v[194:197], v148 offset:3072
	ds_read_b128 v[198:201], v148 offset:4096
	ds_read_b128 v[202:205], v148 offset:5120
	ds_read_b128 v[206:209], v148 offset:6144
	ds_read_b128 v[210:213], v148 offset:7168
	global_load_lds_dwordx4 v[144:145], off
	v_lshl_add_u64 v[144:145], s[40:41], 0, v[142:143]
	s_add_i32 m0, s69, 0xe000
	s_nop 0
	global_load_lds_dwordx4 v[144:145], off
	s_waitcnt vmcnt(8)
	s_waitcnt lgkmcnt(0)
	s_setprio 1
	s_barrier
	v_mfma_f32_16x16x32_bf16 v[126:129], v[150:153], v[182:185], 0
	v_mfma_f32_16x16x32_bf16 v[122:125], v[158:161], v[182:185], 0
	v_mfma_f32_16x16x32_bf16 v[110:113], v[150:153], v[190:193], 0
	v_mfma_f32_16x16x32_bf16 v[106:109], v[158:161], v[190:193], 0
	v_mfma_f32_16x16x32_bf16 v[94:97], v[150:153], v[198:201], 0
	v_mfma_f32_16x16x32_bf16 v[90:93], v[158:161], v[198:201], 0
	v_mfma_f32_16x16x32_bf16 v[78:81], v[150:153], v[206:209], 0
	v_mfma_f32_16x16x32_bf16 v[74:77], v[158:161], v[206:209], 0
	v_mfma_f32_16x16x32_bf16 v[126:129], v[154:157], v[186:189], v[126:129]
	v_mfma_f32_16x16x32_bf16 v[122:125], v[162:165], v[186:189], v[122:125]
	v_mfma_f32_16x16x32_bf16 v[110:113], v[154:157], v[194:197], v[110:113]
	v_mfma_f32_16x16x32_bf16 v[106:109], v[162:165], v[194:197], v[106:109]
	v_mfma_f32_16x16x32_bf16 v[94:97], v[154:157], v[202:205], v[94:97]
	v_mfma_f32_16x16x32_bf16 v[90:93], v[162:165], v[202:205], v[90:93]
	v_mfma_f32_16x16x32_bf16 v[78:81], v[154:157], v[210:213], v[78:81]
	v_mfma_f32_16x16x32_bf16 v[74:77], v[162:165], v[210:213], v[74:77]
	v_mfma_f32_16x16x32_bf16 v[118:121], v[166:169], v[182:185], 0
	v_mfma_f32_16x16x32_bf16 v[114:117], v[174:177], v[182:185], 0
	v_mfma_f32_16x16x32_bf16 v[102:105], v[166:169], v[190:193], 0
	v_mfma_f32_16x16x32_bf16 v[98:101], v[174:177], v[190:193], 0
	v_mfma_f32_16x16x32_bf16 v[86:89], v[166:169], v[198:201], 0
	v_mfma_f32_16x16x32_bf16 v[82:85], v[174:177], v[198:201], 0
	v_mfma_f32_16x16x32_bf16 v[70:73], v[166:169], v[206:209], 0
	v_mfma_f32_16x16x32_bf16 v[66:69], v[174:177], v[206:209], 0
	v_mfma_f32_16x16x32_bf16 v[118:121], v[170:173], v[186:189], v[118:121]
	v_mfma_f32_16x16x32_bf16 v[114:117], v[178:181], v[186:189], v[114:117]
	v_mfma_f32_16x16x32_bf16 v[102:105], v[170:173], v[194:197], v[102:105]
	v_mfma_f32_16x16x32_bf16 v[98:101], v[178:181], v[194:197], v[98:101]
	v_mfma_f32_16x16x32_bf16 v[86:89], v[170:173], v[202:205], v[86:89]
	v_mfma_f32_16x16x32_bf16 v[82:85], v[178:181], v[202:205], v[82:85]
	v_mfma_f32_16x16x32_bf16 v[70:73], v[170:173], v[210:213], v[70:73]
	v_mfma_f32_16x16x32_bf16 v[66:69], v[178:181], v[210:213], v[66:69]
	s_barrier
	s_setprio 0
	s_add_i32 s6, s95, s50
	v_lshl_add_u64 v[144:145], s[16:17], 0, v[134:135]
	s_mov_b32 m0, s6
	ds_read_b128 v[182:185], v148 offset:16384
	ds_read_b128 v[186:189], v148 offset:17408
	ds_read_b128 v[190:193], v148 offset:18432
	ds_read_b128 v[194:197], v148 offset:19456
	ds_read_b128 v[198:201], v148 offset:20480
	ds_read_b128 v[202:205], v148 offset:21504
	ds_read_b128 v[206:209], v148 offset:22528
	ds_read_b128 v[210:213], v148 offset:23552
	global_load_lds_dwordx4 v[144:145], off
	s_add_i32 m0, s6, 0x2000
	s_add_u32 s6, s16, 0x100000
	v_lshl_add_u64 v[214:215], s[16:17], 0, v[130:131]
	s_addc_u32 s7, s17, 0
	s_add_i32 s95, vcc_lo, s50
	global_load_lds_dwordx4 v[214:215], off
	v_lshl_add_u64 v[216:217], s[6:7], 0, v[134:135]
	s_mov_b32 m0, s95
	v_lshl_add_u64 v[218:219], s[42:43], 0, v[132:133]
	global_load_lds_dwordx4 v[216:217], off
	v_lshl_add_u64 v[216:217], s[6:7], 0, v[130:131]
	s_add_i32 m0, s95, 0x2000
	s_nop 0
	global_load_lds_dwordx4 v[216:217], off
	v_lshl_add_u64 v[216:217], s[42:43], 0, v[136:137]
	s_mov_b32 m0, s69
	s_nop 0
	global_load_lds_dwordx4 v[216:217], off
	s_mov_b32 m0, s72
	s_nop 0
	global_load_lds_dwordx4 v[218:219], off
	s_waitcnt vmcnt(8)
	s_waitcnt lgkmcnt(0)
	s_setprio 1
	s_barrier
; #define PG8_STAGEA(bufoff, gbase, voff) PG8_STAGE_X(bufoff, gbase, voff, AUXA)
; #define PG8_STAGEB(bufoff, gbase, voff) PG8_STAGE_X(bufoff, gbase, voff, AUXB)
; #define PG8_LDA(dst, b, h) do { _Pragma("unroll") for (int m = 0; m < 4; ++m) _Pragma("unroll") for (int k = 0; k < 2; ++k) dst[m][k] = *(const PG8_LAS bf16x8*)(lds + PG8_SA(b, h) + aoff + m * 2048 + k * 1024); } while (0)
; #define PG8_LDB(dst, b, h) do { _Pragma("unroll") for (int n = 0; n < 2; ++n) _Pragma("unroll") for (int k = 0; k < 2; ++k) dst[n][k] = *(const PG8_LAS bf16x8*)(lds + PG8_SB(b, h) + boff + n * 2048 + k * 1024); } while (0)
; #define PG8_MMA(ai, bj, At, Bt) do { if (GEMM_PRIO_MODE == 0) __builtin_amdgcn_s_setprio(1); PG8_MMA_LOOPS \
;         acc[ai][bj][m][n] = __builtin_amdgcn_mfma_f32_16x16x32_bf16(Bt[n][k], At[m][k], acc[ai][bj][m][n], 0, 0, 0); if (GEMM_PRIO_MODE == 0) __builtin_amdgcn_s_setprio(0); } while (0)
; #define PG8_WAIT_V(n) asm volatile("s_waitcnt vmcnt(" #n ")" ::: "memory")
; #define PG8_WAIT_VR(n, nr, flag) asm volatile("s_cmp_eq_u32 %0, 0\n\ts_cbranch_scc1 .Lpg8s%=\n\ts_waitcnt vmcnt(" #nr ")\n\ts_branch .Lpg8d%=\n.Lpg8s%=:\n\ts_waitcnt vmcnt(" #n ")\n.Lpg8d%=:" :: "s"(flag) : "memory", "scc")
; #define PG8_WAIT_L(n) asm volatile("s_waitcnt lgkmcnt(" #n ")" ::: "memory")
; #define PG8_BAR __builtin_amdgcn_s_barrier()
; #define PG8_SCHED __builtin_amdgcn_sched_barrier(0)
;     ...
;             PG8_LDA(At, 0, 1); PG8_STAGEB(PG8_SB(0, 0), b2, voffB); PG8_STAGEB(PG8_SB(0, 1), b2 + hstepB, voffB); PG8_STAGEA(PG8_SA(0, 0), a2, voffA);
;     ...
;             PG8_WAIT_VR(8, 24, relax); PG8_WAIT_L(0); PG8_BAR; PG8_MMA(1, 0, At, B0); PG8_MMA(1, 1, At, B1); PG8_BAR; PG8_SCHED;
;     ...
;             PG8_WAIT_V(8); PG8_WAIT_L(0); PG8_BAR; PG8_MMA(1, 0, At, B0); PG8_MMA(1, 1, At, B1); PG8_BAR; PG8_SCHED;
;     ...
;             PG8_LDB(B0, 1, 0); PG8_LDB(B1, 1, 1); PG8_SCHED; PG8_LDA(At, 1, 0); PG8_STAGEA(PG8_SA(0, 1), a2 + hstepA, voffA);
;             PG8_WAIT_V(8); PG8_WAIT_L(0); PG8_BAR; PG8_MMA(0, 0, At, B0); PG8_MMA(0, 1, At, B1); PG8_BAR; PG8_SCHED;
	v_mfma_f32_16x16x32_bf16 v[62:65], v[150:153], v[182:185], 0
	v_mfma_f32_16x16x32_bf16 v[58:61], v[158:161], v[182:185], 0
	v_mfma_f32_16x16x32_bf16 v[46:49], v[150:153], v[190:193], 0
	v_mfma_f32_16x16x32_bf16 v[42:45], v[158:161], v[190:193], 0
	v_mfma_f32_16x16x32_bf16 v[30:33], v[150:153], v[198:201], 0
	v_mfma_f32_16x16x32_bf16 v[26:29], v[158:161], v[198:201], 0
	v_mfma_f32_16x16x32_bf16 v[12:15], v[150:153], v[206:209], 0
	v_mfma_f32_16x16x32_bf16 v[8:11], v[158:161], v[206:209], 0
	v_mfma_f32_16x16x32_bf16 v[62:65], v[154:157], v[186:189], v[62:65]
	v_mfma_f32_16x16x32_bf16 v[58:61], v[162:165], v[186:189], v[58:61]
	v_mfma_f32_16x16x32_bf16 v[46:49], v[154:157], v[194:197], v[46:49]
	v_mfma_f32_16x16x32_bf16 v[42:45], v[162:165], v[194:197], v[42:45]
	v_mfma_f32_16x16x32_bf16 v[30:33], v[154:157], v[202:205], v[30:33]
	v_mfma_f32_16x16x32_bf16 v[26:29], v[162:165], v[202:205], v[26:29]
	v_mfma_f32_16x16x32_bf16 v[12:15], v[154:157], v[210:213], v[12:15]
	v_mfma_f32_16x16x32_bf16 v[8:11], v[162:165], v[210:213], v[8:11]
	v_mfma_f32_16x16x32_bf16 v[54:57], v[166:169], v[182:185], 0
	v_mfma_f32_16x16x32_bf16 v[50:53], v[174:177], v[182:185], 0
	v_mfma_f32_16x16x32_bf16 v[38:41], v[166:169], v[190:193], 0
	v_mfma_f32_16x16x32_bf16 v[34:37], v[174:177], v[190:193], 0
	v_mfma_f32_16x16x32_bf16 v[22:25], v[166:169], v[198:201], 0
	v_mfma_f32_16x16x32_bf16 v[18:21], v[174:177], v[198:201], 0
	v_mfma_f32_16x16x32_bf16 v[4:7], v[166:169], v[206:209], 0
	v_mfma_f32_16x16x32_bf16 v[0:3], v[174:177], v[206:209], 0
	v_mfma_f32_16x16x32_bf16 v[54:57], v[170:173], v[186:189], v[54:57]
	v_mfma_f32_16x16x32_bf16 v[50:53], v[178:181], v[186:189], v[50:53]
	v_mfma_f32_16x16x32_bf16 v[38:41], v[170:173], v[194:197], v[38:41]
	v_mfma_f32_16x16x32_bf16 v[34:37], v[178:181], v[194:197], v[34:37]
	v_mfma_f32_16x16x32_bf16 v[22:25], v[170:173], v[202:205], v[22:25]
	v_mfma_f32_16x16x32_bf16 v[18:21], v[178:181], v[202:205], v[18:21]
	v_mfma_f32_16x16x32_bf16 v[4:7], v[170:173], v[210:213], v[4:7]
	v_mfma_f32_16x16x32_bf16 v[0:3], v[178:181], v[210:213], v[0:3]
	s_barrier
	s_setprio 0
	s_add_i32 s95, 0, 0x18000
	v_add_u32_e32 v149, s95, v146
	s_add_i32 vcc_lo, 0, 0x1c000
	ds_read_b128 v[150:153], v149
	ds_read_b128 v[154:157], v149 offset:1024
	ds_read_b128 v[158:161], v149 offset:2048
	ds_read_b128 v[162:165], v149 offset:3072
	v_add_u32_e32 v149, vcc_lo, v146
	ds_read_b128 v[166:169], v149
	ds_read_b128 v[170:173], v149 offset:1024
	ds_read_b128 v[174:177], v149 offset:2048
	ds_read_b128 v[178:181], v149 offset:3072
	s_add_u32 s6, s42, 0x100000
	s_addc_u32 s7, s43, 0
	s_mov_b32 m0, s73
	v_lshl_add_u64 v[220:221], s[6:7], 0, v[136:137]
	ds_read_b128 v[182:185], v148 offset:32768
	ds_read_b128 v[186:189], v148 offset:33792
	ds_read_b128 v[190:193], v148 offset:34816
	ds_read_b128 v[194:197], v148 offset:35840
	ds_read_b128 v[198:201], v148 offset:36864
	ds_read_b128 v[202:205], v148 offset:37888
	ds_read_b128 v[206:209], v148 offset:38912
	ds_read_b128 v[210:213], v148 offset:39936
	global_load_lds_dwordx4 v[220:221], off
	v_lshl_add_u64 v[220:221], s[6:7], 0, v[132:133]
	s_mov_b32 m0, s82
	s_nop 0
	global_load_lds_dwordx4 v[220:221], off
	s_waitcnt vmcnt(8)
	s_waitcnt lgkmcnt(0)
	s_setprio 1
	s_barrier
	v_mfma_f32_16x16x32_bf16 v[126:129], v[150:153], v[182:185], v[126:129]
	v_mfma_f32_16x16x32_bf16 v[122:125], v[158:161], v[182:185], v[122:125]
	v_mfma_f32_16x16x32_bf16 v[110:113], v[150:153], v[190:193], v[110:113]
	v_mfma_f32_16x16x32_bf16 v[106:109], v[158:161], v[190:193], v[106:109]
	v_mfma_f32_16x16x32_bf16 v[94:97], v[150:153], v[198:201], v[94:97]
	v_mfma_f32_16x16x32_bf16 v[90:93], v[158:161], v[198:201], v[90:93]
	v_mfma_f32_16x16x32_bf16 v[78:81], v[150:153], v[206:209], v[78:81]
	v_mfma_f32_16x16x32_bf16 v[74:77], v[158:161], v[206:209], v[74:77]
	v_mfma_f32_16x16x32_bf16 v[126:129], v[154:157], v[186:189], v[126:129]
	v_mfma_f32_16x16x32_bf16 v[122:125], v[162:165], v[186:189], v[122:125]
	v_mfma_f32_16x16x32_bf16 v[110:113], v[154:157], v[194:197], v[110:113]
	v_mfma_f32_16x16x32_bf16 v[106:109], v[162:165], v[194:197], v[106:109]
	v_mfma_f32_16x16x32_bf16 v[94:97], v[154:157], v[202:205], v[94:97]
	v_mfma_f32_16x16x32_bf16 v[90:93], v[162:165], v[202:205], v[90:93]
	v_mfma_f32_16x16x32_bf16 v[78:81], v[154:157], v[210:213], v[78:81]
	v_mfma_f32_16x16x32_bf16 v[74:77], v[162:165], v[210:213], v[74:77]
	v_mfma_f32_16x16x32_bf16 v[118:121], v[166:169], v[182:185], v[118:121]
	v_mfma_f32_16x16x32_bf16 v[114:117], v[174:177], v[182:185], v[114:117]
	v_mfma_f32_16x16x32_bf16 v[102:105], v[166:169], v[190:193], v[102:105]
	v_mfma_f32_16x16x32_bf16 v[98:101], v[174:177], v[190:193], v[98:101]
	v_mfma_f32_16x16x32_bf16 v[86:89], v[166:169], v[198:201], v[86:89]
	v_mfma_f32_16x16x32_bf16 v[82:85], v[174:177], v[198:201], v[82:85]
	v_mfma_f32_16x16x32_bf16 v[70:73], v[166:169], v[206:209], v[70:73]
	v_mfma_f32_16x16x32_bf16 v[66:69], v[174:177], v[206:209], v[66:69]
	v_mfma_f32_16x16x32_bf16 v[118:121], v[170:173], v[186:189], v[118:121]
	v_mfma_f32_16x16x32_bf16 v[114:117], v[178:181], v[186:189], v[114:117]
	v_mfma_f32_16x16x32_bf16 v[102:105], v[170:173], v[194:197], v[102:105]
	v_mfma_f32_16x16x32_bf16 v[98:101], v[178:181], v[194:197], v[98:101]
	v_mfma_f32_16x16x32_bf16 v[86:89], v[170:173], v[202:205], v[86:89]
	v_mfma_f32_16x16x32_bf16 v[82:85], v[178:181], v[202:205], v[82:85]
	v_mfma_f32_16x16x32_bf16 v[70:73], v[170:173], v[210:213], v[70:73]
	v_mfma_f32_16x16x32_bf16 v[66:69], v[178:181], v[210:213], v[66:69]
	s_barrier
; #define PG8_STAGEA(bufoff, gbase, voff) PG8_STAGE_X(bufoff, gbase, voff, AUXA)
; #define PG8_STAGEB(bufoff, gbase, voff) PG8_STAGE_X(bufoff, gbase, voff, AUXB)
; #define PG8_LDA(dst, b, h) do { _Pragma("unroll") for (int m = 0; m < 4; ++m) _Pragma("unroll") for (int k = 0; k < 2; ++k) dst[m][k] = *(const PG8_LAS bf16x8*)(lds + PG8_SA(b, h) + aoff + m * 2048 + k * 1024); } while (0)
; #define PG8_LDB(dst, b, h) do { _Pragma("unroll") for (int n = 0; n < 2; ++n) _Pragma("unroll") for (int k = 0; k < 2; ++k) dst[n][k] = *(const PG8_LAS bf16x8*)(lds + PG8_SB(b, h) + boff + n * 2048 + k * 1024); } while (0)
; #define PG8_MMA(ai, bj, At, Bt) do { if (GEMM_PRIO_MODE == 0) __builtin_amdgcn_s_setprio(1); PG8_MMA_LOOPS \
;         acc[ai][bj][m][n] = __builtin_amdgcn_mfma_f32_16x16x32_bf16(Bt[n][k], At[m][k], acc[ai][bj][m][n], 0, 0, 0); if (GEMM_PRIO_MODE == 0) __builtin_amdgcn_s_setprio(0); } while (0)
; #define PG8_WAIT_V(n) asm volatile("s_waitcnt vmcnt(" #n ")" ::: "memory")
; #define PG8_WAIT_L(n) asm volatile("s_waitcnt lgkmcnt(" #n ")" ::: "memory")
; #define PG8_BAR __builtin_amdgcn_s_barrier()
; #define PG8_SCHED __builtin_amdgcn_sched_barrier(0)
;     ...
;         for (int t = t0; t < nt; t += 2) {
;             const bool last = (t == nt - 2);
;             const char* a1 = cA + (size_t)(t + 1) * kstepA;
;             const char* a2 = last ? nA : cA + (size_t)(t + 2) * kstepA; const char* b2 = last ? nB : cB + (size_t)(t + 2) * kstepB;
;             const char* a3 = a2 + kstepA; const char* b3 = b2 + kstepB;
;     ...
;             PG8_LDB(B0, 1, 0); PG8_LDB(B1, 1, 1); PG8_SCHED; PG8_LDA(At, 1, 0); PG8_STAGEA(PG8_SA(0, 1), a2 + hstepA, voffA);
;             PG8_WAIT_V(8); PG8_WAIT_L(0); PG8_BAR; PG8_MMA(0, 0, At, B0); PG8_MMA(0, 1, At, B1); PG8_BAR; PG8_SCHED;
;             PG8_LDA(At, 1, 1); PG8_STAGEB(PG8_SB(1, 0), b3, voffB); PG8_STAGEB(PG8_SB(1, 1), b3 + hstepB, voffB); PG8_STAGEA(PG8_SA(1, 0), a3, voffA);
;             PG8_WAIT_V(8); PG8_WAIT_L(0); PG8_BAR; PG8_MMA(1, 0, At, B0); PG8_MMA(1, 1, At, B1); PG8_BAR; PG8_SCHED;
	s_setprio 0
	s_add_i32 s6, s95, s50
	v_lshl_add_u64 v[144:145], v[144:145], 0, s[86:87]
	s_mov_b32 m0, s6
	ds_read_b128 v[182:185], v148 offset:49152
	ds_read_b128 v[186:189], v148 offset:50176
	ds_read_b128 v[190:193], v148 offset:51200
	ds_read_b128 v[194:197], v148 offset:52224
	ds_read_b128 v[198:201], v148 offset:53248
	ds_read_b128 v[202:205], v148 offset:54272
	ds_read_b128 v[206:209], v148 offset:55296
	ds_read_b128 v[210:213], v148 offset:56320
	global_load_lds_dwordx4 v[144:145], off
	s_add_i32 m0, s6, 0x2000
	s_add_u32 s6, s16, 0x100080
	v_lshl_add_u64 v[144:145], v[214:215], 0, s[86:87]
	s_addc_u32 s7, s17, 0
	s_add_i32 s16, vcc_lo, s50
	global_load_lds_dwordx4 v[144:145], off
	v_lshl_add_u64 v[144:145], s[6:7], 0, v[134:135]
	s_mov_b32 m0, s16
	s_nop 0
	global_load_lds_dwordx4 v[144:145], off
	v_lshl_add_u64 v[144:145], s[6:7], 0, v[130:131]
	s_add_i32 m0, s16, 0x2000
	s_nop 0
	global_load_lds_dwordx4 v[144:145], off
	v_lshl_add_u64 v[144:145], v[216:217], 0, s[86:87]
	s_mov_b32 m0, s83
	s_nop 0
	global_load_lds_dwordx4 v[144:145], off
	v_lshl_add_u64 v[144:145], v[218:219], 0, s[86:87]
	s_mov_b32 m0, s90
	s_nop 0
	global_load_lds_dwordx4 v[144:145], off
	s_waitcnt vmcnt(8)
	s_waitcnt lgkmcnt(0)
	s_setprio 1
	s_barrier
	v_mfma_f32_16x16x32_bf16 v[62:65], v[150:153], v[182:185], v[62:65]
	v_mfma_f32_16x16x32_bf16 v[58:61], v[158:161], v[182:185], v[58:61]
	v_mfma_f32_16x16x32_bf16 v[46:49], v[150:153], v[190:193], v[46:49]
	v_mfma_f32_16x16x32_bf16 v[42:45], v[158:161], v[190:193], v[42:45]
	v_mfma_f32_16x16x32_bf16 v[30:33], v[150:153], v[198:201], v[30:33]
	v_mfma_f32_16x16x32_bf16 v[26:29], v[158:161], v[198:201], v[26:29]
	v_mfma_f32_16x16x32_bf16 v[12:15], v[150:153], v[206:209], v[12:15]
	v_mfma_f32_16x16x32_bf16 v[8:11], v[158:161], v[206:209], v[8:11]
	v_mfma_f32_16x16x32_bf16 v[62:65], v[154:157], v[186:189], v[62:65]
	v_mfma_f32_16x16x32_bf16 v[58:61], v[162:165], v[186:189], v[58:61]
	v_mfma_f32_16x16x32_bf16 v[46:49], v[154:157], v[194:197], v[46:49]
	v_mfma_f32_16x16x32_bf16 v[42:45], v[162:165], v[194:197], v[42:45]
	v_mfma_f32_16x16x32_bf16 v[30:33], v[154:157], v[202:205], v[30:33]
	v_mfma_f32_16x16x32_bf16 v[26:29], v[162:165], v[202:205], v[26:29]
	v_mfma_f32_16x16x32_bf16 v[12:15], v[154:157], v[210:213], v[12:15]
	v_mfma_f32_16x16x32_bf16 v[8:11], v[162:165], v[210:213], v[8:11]
	v_mfma_f32_16x16x32_bf16 v[54:57], v[166:169], v[182:185], v[54:57]
	v_mfma_f32_16x16x32_bf16 v[50:53], v[174:177], v[182:185], v[50:53]
	v_mfma_f32_16x16x32_bf16 v[38:41], v[166:169], v[190:193], v[38:41]
	v_mfma_f32_16x16x32_bf16 v[34:37], v[174:177], v[190:193], v[34:37]
	v_mfma_f32_16x16x32_bf16 v[22:25], v[166:169], v[198:201], v[22:25]
	v_mfma_f32_16x16x32_bf16 v[18:21], v[174:177], v[198:201], v[18:21]
	v_mfma_f32_16x16x32_bf16 v[4:7], v[166:169], v[206:209], v[4:7]
	v_mfma_f32_16x16x32_bf16 v[0:3], v[174:177], v[206:209], v[0:3]
	v_mfma_f32_16x16x32_bf16 v[54:57], v[170:173], v[186:189], v[54:57]
	v_mfma_f32_16x16x32_bf16 v[50:53], v[178:181], v[186:189], v[50:53]
	v_mfma_f32_16x16x32_bf16 v[38:41], v[170:173], v[194:197], v[38:41]
	v_mfma_f32_16x16x32_bf16 v[34:37], v[178:181], v[194:197], v[34:37]
	v_mfma_f32_16x16x32_bf16 v[22:25], v[170:173], v[202:205], v[22:25]
	v_mfma_f32_16x16x32_bf16 v[18:21], v[178:181], v[202:205], v[18:21]
	v_mfma_f32_16x16x32_bf16 v[4:7], v[170:173], v[210:213], v[4:7]
	v_mfma_f32_16x16x32_bf16 v[0:3], v[178:181], v[210:213], v[0:3]
	s_barrier
	s_setprio 0
	s_add_i32 s39, s39, 2
	s_add_u32 s40, s40, 0x100
	s_addc_u32 s41, s41, 0
	s_add_u32 s12, s12, 0x100
	s_addc_u32 s13, s13, 0

; #define PG8_STAGEA(bufoff, gbase, voff) PG8_STAGE_X(bufoff, gbase, voff, AUXA)
; #define PG8_STAGEB(bufoff, gbase, voff) PG8_STAGE_X(bufoff, gbase, voff, AUXB)
; #define PG8_LDA(dst, b, h) do { _Pragma("unroll") for (int m = 0; m < 4; ++m) _Pragma("unroll") for (int k = 0; k < 2; ++k) dst[m][k] = *(const PG8_LAS bf16x8*)(lds + PG8_SA(b, h) + aoff + m * 2048 + k * 1024); } while (0)
; #define PG8_LDB(dst, b, h) do { _Pragma("unroll") for (int n = 0; n < 2; ++n) _Pragma("unroll") for (int k = 0; k < 2; ++k) dst[n][k] = *(const PG8_LAS bf16x8*)(lds + PG8_SB(b, h) + boff + n * 2048 + k * 1024); } while (0)
; #define PG8_MMA(ai, bj, At, Bt) do { if (GEMM_PRIO_MODE == 0) __builtin_amdgcn_s_setprio(1); PG8_MMA_LOOPS \
;         acc[ai][bj][m][n] = __builtin_amdgcn_mfma_f32_16x16x32_bf16(Bt[n][k], At[m][k], acc[ai][bj][m][n], 0, 0, 0); if (GEMM_PRIO_MODE == 0) __builtin_amdgcn_s_setprio(0); } while (0)
; #define PG8_WAIT_V(n) asm volatile("s_waitcnt vmcnt(" #n ")" ::: "memory")
; #define PG8_WAIT_L(n) asm volatile("s_waitcnt lgkmcnt(" #n ")" ::: "memory")
;     ...
;         for (int t = t0; t < nt; t += 2) {
;             const bool last = (t == nt - 2);
;             const char* a1 = cA + (size_t)(t + 1) * kstepA;
;             const char* a2 = last ? nA : cA + (size_t)(t + 2) * kstepA; const char* b2 = last ? nB : cB + (size_t)(t + 2) * kstepB;
;             const char* a3 = a2 + kstepA; const char* b3 = b2 + kstepB;
;             if (last && has_next) S.a_ready(nxt);
;             if constexpr (SP2) {
;             PG8_LDB(B0, 0, 0); PG8_LDB(B1, 0, 1); PG8_SCHED; PG8_LDA(At, 0, 0); PG8_STAGEA(PG8_SA(1, 1), a1 + hstepA, voffA);
;     ...
;             const int relax = __builtin_amdgcn_readfirstlane((t == 0 && ui > 0) ? 1 : 0);
;             PG8_WAIT_VR(8, 24, relax); PG8_WAIT_L(0); PG8_BAR; PG8_MMA(0, 0, At, B0); PG8_MMA(0, 1, At, B1); PG8_BAR; PG8_SCHED;
;     ...
;             PG8_WAIT_V(8); PG8_WAIT_L(0); PG8_BAR; PG8_MMA(0, 0, At, B0); PG8_MMA(0, 1, At, B1); PG8_BAR; PG8_SCHED;
;     ...
;             PG8_LDA(At, 0, 1); PG8_STAGEB(PG8_SB(0, 0), b2, voffB); PG8_STAGEB(PG8_SB(0, 1), b2 + hstepB, voffB); PG8_STAGEA(PG8_SA(0, 0), a2, voffA);
;     ...
;             PG8_WAIT_VR(8, 24, relax); PG8_WAIT_L(0); PG8_BAR; PG8_MMA(1, 0, At, B0); PG8_MMA(1, 1, At, B1); PG8_BAR; PG8_SCHED;
;     ...
;             PG8_WAIT_V(8); PG8_WAIT_L(0); PG8_BAR; PG8_MMA(1, 0, At, B0); PG8_MMA(1, 1, At, B1); PG8_BAR; PG8_SCHED;
.LBB0_847:
	s_ashr_i32 s11, s10, 31
	s_lshl_b64 s[18:19], s[10:11], 23
	s_add_u32 s18, s62, s18
	s_addc_u32 s19, s63, s19
	s_and_b64 s[22:23], s[20:21], exec
	s_cselect_b32 s11, s19, s1
	s_cselect_b32 s73, s18, s0
	s_ashr_i32 s15, s14, 31
	s_lshl_b64 s[22:23], s[14:15], 23
	s_add_u32 s22, s12, s22
	s_addc_u32 s23, s13, s23
	s_and_b64 s[24:25], s[20:21], exec
	s_cselect_b32 s15, s23, s17
	s_cselect_b32 s78, s22, s16
	s_add_u32 s24, s0, 0xc000
	s_addc_u32 s25, s1, 0
	s_add_u32 s0, s16, 0x10000
	s_addc_u32 s1, s17, 0
	s_mov_b32 s82, -2
	s_waitcnt lgkmcnt(0)
	s_add_u32 s16, s24, 0x4000
	s_addc_u32 s17, s25, 0
	s_cmpk_eq_i32 s82, 0xfc
	s_cselect_b32 s36, s73, s16
	s_cselect_b32 s37, s11, s17
	s_cselect_b32 s16, s78, s0
	s_cselect_b32 s17, s15, s1
	s_add_u32 s26, s36, 0x8000
	s_addc_u32 s27, s37, 0
	s_add_i32 s83, 0, 0x10000
	s_add_i32 s94, 0, 0x14000
	v_add_u32_e32 v152, s83, v157
	v_add_u32_e32 v174, s94, v157
	ds_read_b128 v[130:133], v152
	ds_read_b128 v[134:137], v152 offset:1024
	ds_read_b128 v[148:151], v152 offset:2048
	ds_read_b128 v[152:155], v152 offset:3072
	ds_read_b128 v[162:165], v174
	ds_read_b128 v[166:169], v174 offset:1024
	ds_read_b128 v[170:173], v174 offset:2048
	ds_read_b128 v[174:177], v174 offset:3072
	v_lshl_add_u64 v[210:211], s[24:25], 0, v[144:145]
	s_add_i32 m0, s39, 0xc000
	ds_read_b128 v[178:181], v161
	ds_read_b128 v[182:185], v161 offset:1024
	ds_read_b128 v[186:189], v161 offset:2048
	ds_read_b128 v[190:193], v161 offset:3072
	ds_read_b128 v[194:197], v161 offset:4096
	ds_read_b128 v[198:201], v161 offset:5120
	ds_read_b128 v[202:205], v161 offset:6144
	ds_read_b128 v[206:209], v161 offset:7168
	global_load_lds_dwordx4 v[210:211], off
	v_lshl_add_u64 v[210:211], s[24:25], 0, v[146:147]
	s_add_i32 m0, s39, 0xe000
	s_nop 0
	global_load_lds_dwordx4 v[210:211], off
	s_waitcnt vmcnt(8)
	s_waitcnt lgkmcnt(0)
	s_setprio 1
	s_barrier
	v_mfma_f32_16x16x32_bf16 v[126:129], v[130:133], v[178:181], 0
	v_mfma_f32_16x16x32_bf16 v[122:125], v[148:151], v[178:181], 0
	v_mfma_f32_16x16x32_bf16 v[110:113], v[130:133], v[186:189], 0
	v_mfma_f32_16x16x32_bf16 v[106:109], v[148:151], v[186:189], 0
	v_mfma_f32_16x16x32_bf16 v[94:97], v[130:133], v[194:197], 0
	v_mfma_f32_16x16x32_bf16 v[90:93], v[148:151], v[194:197], 0
	v_mfma_f32_16x16x32_bf16 v[78:81], v[130:133], v[202:205], 0
	v_mfma_f32_16x16x32_bf16 v[74:77], v[148:151], v[202:205], 0
	v_mfma_f32_16x16x32_bf16 v[126:129], v[134:137], v[182:185], v[126:129]
	v_mfma_f32_16x16x32_bf16 v[122:125], v[152:155], v[182:185], v[122:125]
	v_mfma_f32_16x16x32_bf16 v[110:113], v[134:137], v[190:193], v[110:113]
	v_mfma_f32_16x16x32_bf16 v[106:109], v[152:155], v[190:193], v[106:109]
	v_mfma_f32_16x16x32_bf16 v[94:97], v[134:137], v[198:201], v[94:97]
	v_mfma_f32_16x16x32_bf16 v[90:93], v[152:155], v[198:201], v[90:93]
	v_mfma_f32_16x16x32_bf16 v[78:81], v[134:137], v[206:209], v[78:81]
	v_mfma_f32_16x16x32_bf16 v[74:77], v[152:155], v[206:209], v[74:77]
	v_mfma_f32_16x16x32_bf16 v[118:121], v[162:165], v[178:181], 0
	v_mfma_f32_16x16x32_bf16 v[114:117], v[170:173], v[178:181], 0
	v_mfma_f32_16x16x32_bf16 v[102:105], v[162:165], v[186:189], 0
	v_mfma_f32_16x16x32_bf16 v[98:101], v[170:173], v[186:189], 0
	v_mfma_f32_16x16x32_bf16 v[86:89], v[162:165], v[194:197], 0
	v_mfma_f32_16x16x32_bf16 v[82:85], v[170:173], v[194:197], 0
	v_mfma_f32_16x16x32_bf16 v[70:73], v[162:165], v[202:205], 0
	v_mfma_f32_16x16x32_bf16 v[66:69], v[170:173], v[202:205], 0
	v_mfma_f32_16x16x32_bf16 v[118:121], v[166:169], v[182:185], v[118:121]
	v_mfma_f32_16x16x32_bf16 v[114:117], v[174:177], v[182:185], v[114:117]
	v_mfma_f32_16x16x32_bf16 v[102:105], v[166:169], v[190:193], v[102:105]
	v_mfma_f32_16x16x32_bf16 v[98:101], v[174:177], v[190:193], v[98:101]
	v_mfma_f32_16x16x32_bf16 v[86:89], v[166:169], v[198:201], v[86:89]
	v_mfma_f32_16x16x32_bf16 v[82:85], v[174:177], v[198:201], v[82:85]
	v_mfma_f32_16x16x32_bf16 v[70:73], v[166:169], v[206:209], v[70:73]
	v_mfma_f32_16x16x32_bf16 v[66:69], v[174:177], v[206:209], v[66:69]
	s_barrier
	s_setprio 0
	s_add_i32 s83, s83, s38
	v_lshl_add_u64 v[210:211], s[16:17], 0, v[16:17]
	s_mov_b32 m0, s83
	ds_read_b128 v[178:181], v161 offset:16384
	ds_read_b128 v[182:185], v161 offset:17408
	ds_read_b128 v[186:189], v161 offset:18432
	ds_read_b128 v[190:193], v161 offset:19456
	ds_read_b128 v[194:197], v161 offset:20480
	ds_read_b128 v[198:201], v161 offset:21504
	ds_read_b128 v[202:205], v161 offset:22528
	ds_read_b128 v[206:209], v161 offset:23552
	global_load_lds_dwordx4 v[210:211], off
	s_add_i32 m0, s83, 0x2000
	s_add_u32 s90, s16, 0x4000
	v_lshl_add_u64 v[210:211], s[16:17], 0, v[138:139]
	s_addc_u32 s91, s17, 0
	s_add_i32 s83, s94, s38
	global_load_lds_dwordx4 v[210:211], off
	v_lshl_add_u64 v[210:211], s[90:91], 0, v[16:17]
	s_mov_b32 m0, s83
	s_nop 0
	global_load_lds_dwordx4 v[210:211], off
	v_lshl_add_u64 v[210:211], s[90:91], 0, v[138:139]
	s_add_i32 m0, s83, 0x2000
	s_nop 0
	global_load_lds_dwordx4 v[210:211], off
	v_lshl_add_u64 v[210:211], s[36:37], 0, v[142:143]
	s_mov_b32 m0, s39
	s_nop 0
	global_load_lds_dwordx4 v[210:211], off
	v_lshl_add_u64 v[210:211], s[36:37], 0, v[140:141]
	s_mov_b32 m0, s40
	s_nop 0
	global_load_lds_dwordx4 v[210:211], off
	s_waitcnt vmcnt(8)
	s_waitcnt lgkmcnt(0)
	s_setprio 1
	s_barrier
; #define PG8_STAGEA(bufoff, gbase, voff) PG8_STAGE_X(bufoff, gbase, voff, AUXA)
; #define PG8_STAGEB(bufoff, gbase, voff) PG8_STAGE_X(bufoff, gbase, voff, AUXB)
; #define PG8_LDA(dst, b, h) do { _Pragma("unroll") for (int m = 0; m < 4; ++m) _Pragma("unroll") for (int k = 0; k < 2; ++k) dst[m][k] = *(const PG8_LAS bf16x8*)(lds + PG8_SA(b, h) + aoff + m * 2048 + k * 1024); } while (0)
; #define PG8_LDB(dst, b, h) do { _Pragma("unroll") for (int n = 0; n < 2; ++n) _Pragma("unroll") for (int k = 0; k < 2; ++k) dst[n][k] = *(const PG8_LAS bf16x8*)(lds + PG8_SB(b, h) + boff + n * 2048 + k * 1024); } while (0)
; #define PG8_MMA(ai, bj, At, Bt) do { if (GEMM_PRIO_MODE == 0) __builtin_amdgcn_s_setprio(1); PG8_MMA_LOOPS \
;         acc[ai][bj][m][n] = __builtin_amdgcn_mfma_f32_16x16x32_bf16(Bt[n][k], At[m][k], acc[ai][bj][m][n], 0, 0, 0); if (GEMM_PRIO_MODE == 0) __builtin_amdgcn_s_setprio(0); } while (0)
; #define PG8_WAIT_V(n) asm volatile("s_waitcnt vmcnt(" #n ")" ::: "memory")
; #define PG8_WAIT_VR(n, nr, flag) asm volatile("s_cmp_eq_u32 %0, 0\n\ts_cbranch_scc1 .Lpg8s%=\n\ts_waitcnt vmcnt(" #nr ")\n\ts_branch .Lpg8d%=\n.Lpg8s%=:\n\ts_waitcnt vmcnt(" #n ")\n.Lpg8d%=:" :: "s"(flag) : "memory", "scc")
; #define PG8_WAIT_L(n) asm volatile("s_waitcnt lgkmcnt(" #n ")" ::: "memory")
; #define PG8_BAR __builtin_amdgcn_s_barrier()
; #define PG8_SCHED __builtin_amdgcn_sched_barrier(0)
;     ...
;             PG8_LDA(At, 0, 1); PG8_STAGEB(PG8_SB(0, 0), b2, voffB); PG8_STAGEB(PG8_SB(0, 1), b2 + hstepB, voffB); PG8_STAGEA(PG8_SA(0, 0), a2, voffA);
;     ...
;             PG8_WAIT_VR(8, 24, relax); PG8_WAIT_L(0); PG8_BAR; PG8_MMA(1, 0, At, B0); PG8_MMA(1, 1, At, B1); PG8_BAR; PG8_SCHED;
;     ...
;             PG8_WAIT_V(8); PG8_WAIT_L(0); PG8_BAR; PG8_MMA(1, 0, At, B0); PG8_MMA(1, 1, At, B1); PG8_BAR; PG8_SCHED;
;     ...
;             PG8_LDB(B0, 1, 0); PG8_LDB(B1, 1, 1); PG8_SCHED; PG8_LDA(At, 1, 0); PG8_STAGEA(PG8_SA(0, 1), a2 + hstepA, voffA);
;             PG8_WAIT_V(8); PG8_WAIT_L(0); PG8_BAR; PG8_MMA(0, 0, At, B0); PG8_MMA(0, 1, At, B1); PG8_BAR; PG8_SCHED;
	v_mfma_f32_16x16x32_bf16 v[62:65], v[130:133], v[178:181], 0
	v_mfma_f32_16x16x32_bf16 v[58:61], v[148:151], v[178:181], 0
	v_mfma_f32_16x16x32_bf16 v[46:49], v[130:133], v[186:189], 0
	v_mfma_f32_16x16x32_bf16 v[42:45], v[148:151], v[186:189], 0
	v_mfma_f32_16x16x32_bf16 v[30:33], v[130:133], v[194:197], 0
	v_mfma_f32_16x16x32_bf16 v[26:29], v[148:151], v[194:197], 0
	v_mfma_f32_16x16x32_bf16 v[12:15], v[130:133], v[202:205], 0
	v_mfma_f32_16x16x32_bf16 v[8:11], v[148:151], v[202:205], 0
	v_mfma_f32_16x16x32_bf16 v[62:65], v[134:137], v[182:185], v[62:65]
	v_mfma_f32_16x16x32_bf16 v[58:61], v[152:155], v[182:185], v[58:61]
	v_mfma_f32_16x16x32_bf16 v[46:49], v[134:137], v[190:193], v[46:49]
	v_mfma_f32_16x16x32_bf16 v[42:45], v[152:155], v[190:193], v[42:45]
	v_mfma_f32_16x16x32_bf16 v[30:33], v[134:137], v[198:201], v[30:33]
	v_mfma_f32_16x16x32_bf16 v[26:29], v[152:155], v[198:201], v[26:29]
	v_mfma_f32_16x16x32_bf16 v[12:15], v[134:137], v[206:209], v[12:15]
	v_mfma_f32_16x16x32_bf16 v[8:11], v[152:155], v[206:209], v[8:11]
	v_mfma_f32_16x16x32_bf16 v[54:57], v[162:165], v[178:181], 0
	v_mfma_f32_16x16x32_bf16 v[50:53], v[170:173], v[178:181], 0
	v_mfma_f32_16x16x32_bf16 v[38:41], v[162:165], v[186:189], 0
	v_mfma_f32_16x16x32_bf16 v[34:37], v[170:173], v[186:189], 0
	v_mfma_f32_16x16x32_bf16 v[22:25], v[162:165], v[194:197], 0
	v_mfma_f32_16x16x32_bf16 v[18:21], v[170:173], v[194:197], 0
	v_mfma_f32_16x16x32_bf16 v[4:7], v[162:165], v[202:205], 0
	v_mfma_f32_16x16x32_bf16 v[0:3], v[170:173], v[202:205], 0
	v_mfma_f32_16x16x32_bf16 v[54:57], v[166:169], v[182:185], v[54:57]
	v_mfma_f32_16x16x32_bf16 v[50:53], v[174:177], v[182:185], v[50:53]
	v_mfma_f32_16x16x32_bf16 v[38:41], v[166:169], v[190:193], v[38:41]
	v_mfma_f32_16x16x32_bf16 v[34:37], v[174:177], v[190:193], v[34:37]
	v_mfma_f32_16x16x32_bf16 v[22:25], v[166:169], v[198:201], v[22:25]
	v_mfma_f32_16x16x32_bf16 v[18:21], v[174:177], v[198:201], v[18:21]
	v_mfma_f32_16x16x32_bf16 v[4:7], v[166:169], v[206:209], v[4:7]
	v_mfma_f32_16x16x32_bf16 v[0:3], v[174:177], v[206:209], v[0:3]
	s_barrier
	s_setprio 0
	s_add_i32 s83, 0, 0x18000
	s_add_i32 s90, 0, 0x1c000
	v_add_u32_e32 v152, s83, v157
	v_add_u32_e32 v174, s90, v157
	ds_read_b128 v[130:133], v152
	ds_read_b128 v[134:137], v152 offset:1024
	ds_read_b128 v[148:151], v152 offset:2048
	ds_read_b128 v[152:155], v152 offset:3072
	ds_read_b128 v[162:165], v174
	ds_read_b128 v[166:169], v174 offset:1024
	ds_read_b128 v[170:173], v174 offset:2048
	ds_read_b128 v[174:177], v174 offset:3072
	s_add_u32 s36, s36, 0x4000
	s_addc_u32 s37, s37, 0
	s_mov_b32 m0, s41
	v_lshl_add_u64 v[210:211], s[36:37], 0, v[142:143]
	ds_read_b128 v[178:181], v161 offset:32768
	ds_read_b128 v[182:185], v161 offset:33792
	ds_read_b128 v[186:189], v161 offset:34816
	ds_read_b128 v[190:193], v161 offset:35840
	ds_read_b128 v[194:197], v161 offset:36864
	ds_read_b128 v[198:201], v161 offset:37888
	ds_read_b128 v[202:205], v161 offset:38912
	ds_read_b128 v[206:209], v161 offset:39936
	global_load_lds_dwordx4 v[210:211], off
	v_lshl_add_u64 v[210:211], s[36:37], 0, v[140:141]
	s_mov_b32 m0, s42
	s_nop 0
	global_load_lds_dwordx4 v[210:211], off
	s_waitcnt vmcnt(8)
	s_waitcnt lgkmcnt(0)
	s_setprio 1
	s_barrier
	v_mfma_f32_16x16x32_bf16 v[126:129], v[130:133], v[178:181], v[126:129]
	v_mfma_f32_16x16x32_bf16 v[122:125], v[148:151], v[178:181], v[122:125]
	v_mfma_f32_16x16x32_bf16 v[110:113], v[130:133], v[186:189], v[110:113]
	v_mfma_f32_16x16x32_bf16 v[106:109], v[148:151], v[186:189], v[106:109]
	v_mfma_f32_16x16x32_bf16 v[94:97], v[130:133], v[194:197], v[94:97]
	v_mfma_f32_16x16x32_bf16 v[90:93], v[148:151], v[194:197], v[90:93]
	v_mfma_f32_16x16x32_bf16 v[78:81], v[130:133], v[202:205], v[78:81]
	v_mfma_f32_16x16x32_bf16 v[74:77], v[148:151], v[202:205], v[74:77]
	v_mfma_f32_16x16x32_bf16 v[126:129], v[134:137], v[182:185], v[126:129]
	v_mfma_f32_16x16x32_bf16 v[122:125], v[152:155], v[182:185], v[122:125]
	v_mfma_f32_16x16x32_bf16 v[110:113], v[134:137], v[190:193], v[110:113]
	v_mfma_f32_16x16x32_bf16 v[106:109], v[152:155], v[190:193], v[106:109]
	v_mfma_f32_16x16x32_bf16 v[94:97], v[134:137], v[198:201], v[94:97]
	v_mfma_f32_16x16x32_bf16 v[90:93], v[152:155], v[198:201], v[90:93]
	v_mfma_f32_16x16x32_bf16 v[78:81], v[134:137], v[206:209], v[78:81]
	v_mfma_f32_16x16x32_bf16 v[74:77], v[152:155], v[206:209], v[74:77]
	v_mfma_f32_16x16x32_bf16 v[118:121], v[162:165], v[178:181], v[118:121]
	v_mfma_f32_16x16x32_bf16 v[114:117], v[170:173], v[178:181], v[114:117]
	v_mfma_f32_16x16x32_bf16 v[102:105], v[162:165], v[186:189], v[102:105]
	v_mfma_f32_16x16x32_bf16 v[98:101], v[170:173], v[186:189], v[98:101]
	v_mfma_f32_16x16x32_bf16 v[86:89], v[162:165], v[194:197], v[86:89]
	v_mfma_f32_16x16x32_bf16 v[82:85], v[170:173], v[194:197], v[82:85]
	v_mfma_f32_16x16x32_bf16 v[70:73], v[162:165], v[202:205], v[70:73]
	v_mfma_f32_16x16x32_bf16 v[66:69], v[170:173], v[202:205], v[66:69]
	v_mfma_f32_16x16x32_bf16 v[118:121], v[166:169], v[182:185], v[118:121]
	v_mfma_f32_16x16x32_bf16 v[114:117], v[174:177], v[182:185], v[114:117]
	v_mfma_f32_16x16x32_bf16 v[102:105], v[166:169], v[190:193], v[102:105]
	v_mfma_f32_16x16x32_bf16 v[98:101], v[174:177], v[190:193], v[98:101]
	v_mfma_f32_16x16x32_bf16 v[86:89], v[166:169], v[198:201], v[86:89]
	v_mfma_f32_16x16x32_bf16 v[82:85], v[174:177], v[198:201], v[82:85]
	v_mfma_f32_16x16x32_bf16 v[70:73], v[166:169], v[206:209], v[70:73]
	v_mfma_f32_16x16x32_bf16 v[66:69], v[174:177], v[206:209], v[66:69]
	s_barrier
; #define PG8_STAGEA(bufoff, gbase, voff) PG8_STAGE_X(bufoff, gbase, voff, AUXA)
; #define PG8_STAGEB(bufoff, gbase, voff) PG8_STAGE_X(bufoff, gbase, voff, AUXB)
; #define PG8_LDA(dst, b, h) do { _Pragma("unroll") for (int m = 0; m < 4; ++m) _Pragma("unroll") for (int k = 0; k < 2; ++k) dst[m][k] = *(const PG8_LAS bf16x8*)(lds + PG8_SA(b, h) + aoff + m * 2048 + k * 1024); } while (0)
; #define PG8_LDB(dst, b, h) do { _Pragma("unroll") for (int n = 0; n < 2; ++n) _Pragma("unroll") for (int k = 0; k < 2; ++k) dst[n][k] = *(const PG8_LAS bf16x8*)(lds + PG8_SB(b, h) + boff + n * 2048 + k * 1024); } while (0)
; #define PG8_MMA(ai, bj, At, Bt) do { if (GEMM_PRIO_MODE == 0) __builtin_amdgcn_s_setprio(1); PG8_MMA_LOOPS \
;         acc[ai][bj][m][n] = __builtin_amdgcn_mfma_f32_16x16x32_bf16(Bt[n][k], At[m][k], acc[ai][bj][m][n], 0, 0, 0); if (GEMM_PRIO_MODE == 0) __builtin_amdgcn_s_setprio(0); } while (0)
; #define PG8_WAIT_V(n) asm volatile("s_waitcnt vmcnt(" #n ")" ::: "memory")
; #define PG8_WAIT_L(n) asm volatile("s_waitcnt lgkmcnt(" #n ")" ::: "memory")
; #define PG8_BAR __builtin_amdgcn_s_barrier()
; #define PG8_SCHED __builtin_amdgcn_sched_barrier(0)
;     ...
;         for (int t = t0; t < nt; t += 2) {
;             const bool last = (t == nt - 2);
;             const char* a1 = cA + (size_t)(t + 1) * kstepA;
;             const char* a2 = last ? nA : cA + (size_t)(t + 2) * kstepA; const char* b2 = last ? nB : cB + (size_t)(t + 2) * kstepB;
;             const char* a3 = a2 + kstepA; const char* b3 = b2 + kstepB;
;     ...
;             PG8_LDB(B0, 1, 0); PG8_LDB(B1, 1, 1); PG8_SCHED; PG8_LDA(At, 1, 0); PG8_STAGEA(PG8_SA(0, 1), a2 + hstepA, voffA);
;             PG8_WAIT_V(8); PG8_WAIT_L(0); PG8_BAR; PG8_MMA(0, 0, At, B0); PG8_MMA(0, 1, At, B1); PG8_BAR; PG8_SCHED;
;             PG8_LDA(At, 1, 1); PG8_STAGEB(PG8_SB(1, 0), b3, voffB); PG8_STAGEB(PG8_SB(1, 1), b3 + hstepB, voffB); PG8_STAGEA(PG8_SA(1, 0), a3, voffA);
;             PG8_WAIT_V(8); PG8_WAIT_L(0); PG8_BAR; PG8_MMA(1, 0, At, B0); PG8_MMA(1, 1, At, B1); PG8_BAR; PG8_SCHED;
	s_setprio 0
	s_add_u32 s36, s16, 0x8000
	s_addc_u32 s37, s17, 0
	s_add_i32 s83, s83, s38
	v_lshl_add_u64 v[210:211], s[36:37], 0, v[16:17]
	s_mov_b32 m0, s83
	ds_read_b128 v[178:181], v161 offset:49152
	ds_read_b128 v[182:185], v161 offset:50176
	ds_read_b128 v[186:189], v161 offset:51200
	ds_read_b128 v[190:193], v161 offset:52224
	ds_read_b128 v[194:197], v161 offset:53248
	ds_read_b128 v[198:201], v161 offset:54272
	ds_read_b128 v[202:205], v161 offset:55296
	ds_read_b128 v[206:209], v161 offset:56320
	global_load_lds_dwordx4 v[210:211], off
	s_add_i32 m0, s83, 0x2000
	s_add_u32 s16, s16, 0xc000
	v_lshl_add_u64 v[210:211], s[36:37], 0, v[138:139]
	s_addc_u32 s17, s17, 0
	s_add_i32 s36, s90, s38
	global_load_lds_dwordx4 v[210:211], off
	v_lshl_add_u64 v[210:211], s[16:17], 0, v[16:17]
	s_mov_b32 m0, s36
	s_nop 0
	global_load_lds_dwordx4 v[210:211], off
	v_lshl_add_u64 v[210:211], s[16:17], 0, v[138:139]
	s_add_i32 m0, s36, 0x2000
	s_nop 0
	global_load_lds_dwordx4 v[210:211], off
	v_lshl_add_u64 v[210:211], s[26:27], 0, v[142:143]
	s_mov_b32 m0, s50
	s_nop 0
	global_load_lds_dwordx4 v[210:211], off
	v_lshl_add_u64 v[210:211], s[26:27], 0, v[140:141]
	s_mov_b32 m0, s51
	s_nop 0
	global_load_lds_dwordx4 v[210:211], off
	s_waitcnt vmcnt(8)
	s_waitcnt lgkmcnt(0)
	s_setprio 1
	s_barrier
	v_mfma_f32_16x16x32_bf16 v[62:65], v[130:133], v[178:181], v[62:65]
	v_mfma_f32_16x16x32_bf16 v[58:61], v[148:151], v[178:181], v[58:61]
	v_mfma_f32_16x16x32_bf16 v[46:49], v[130:133], v[186:189], v[46:49]
	v_mfma_f32_16x16x32_bf16 v[42:45], v[148:151], v[186:189], v[42:45]
	v_mfma_f32_16x16x32_bf16 v[30:33], v[130:133], v[194:197], v[30:33]
	v_mfma_f32_16x16x32_bf16 v[26:29], v[148:151], v[194:197], v[26:29]
	v_mfma_f32_16x16x32_bf16 v[12:15], v[130:133], v[202:205], v[12:15]
	v_mfma_f32_16x16x32_bf16 v[8:11], v[148:151], v[202:205], v[8:11]
	v_mfma_f32_16x16x32_bf16 v[62:65], v[134:137], v[182:185], v[62:65]
	v_mfma_f32_16x16x32_bf16 v[58:61], v[152:155], v[182:185], v[58:61]
	v_mfma_f32_16x16x32_bf16 v[46:49], v[134:137], v[190:193], v[46:49]
	v_mfma_f32_16x16x32_bf16 v[42:45], v[152:155], v[190:193], v[42:45]
	v_mfma_f32_16x16x32_bf16 v[30:33], v[134:137], v[198:201], v[30:33]
	v_mfma_f32_16x16x32_bf16 v[26:29], v[152:155], v[198:201], v[26:29]
	v_mfma_f32_16x16x32_bf16 v[12:15], v[134:137], v[206:209], v[12:15]
	v_mfma_f32_16x16x32_bf16 v[8:11], v[152:155], v[206:209], v[8:11]
	v_mfma_f32_16x16x32_bf16 v[54:57], v[162:165], v[178:181], v[54:57]
	v_mfma_f32_16x16x32_bf16 v[50:53], v[170:173], v[178:181], v[50:53]
	v_mfma_f32_16x16x32_bf16 v[38:41], v[162:165], v[186:189], v[38:41]
	v_mfma_f32_16x16x32_bf16 v[34:37], v[170:173], v[186:189], v[34:37]
	v_mfma_f32_16x16x32_bf16 v[22:25], v[162:165], v[194:197], v[22:25]
	v_mfma_f32_16x16x32_bf16 v[18:21], v[170:173], v[194:197], v[18:21]
	v_mfma_f32_16x16x32_bf16 v[4:7], v[162:165], v[202:205], v[4:7]
	v_mfma_f32_16x16x32_bf16 v[0:3], v[170:173], v[202:205], v[0:3]
	v_mfma_f32_16x16x32_bf16 v[54:57], v[166:169], v[182:185], v[54:57]
	v_mfma_f32_16x16x32_bf16 v[50:53], v[174:177], v[182:185], v[50:53]
	v_mfma_f32_16x16x32_bf16 v[38:41], v[166:169], v[190:193], v[38:41]
	v_mfma_f32_16x16x32_bf16 v[34:37], v[174:177], v[190:193], v[34:37]
	v_mfma_f32_16x16x32_bf16 v[22:25], v[166:169], v[198:201], v[22:25]
	v_mfma_f32_16x16x32_bf16 v[18:21], v[174:177], v[198:201], v[18:21]
	v_mfma_f32_16x16x32_bf16 v[4:7], v[166:169], v[206:209], v[4:7]
	v_mfma_f32_16x16x32_bf16 v[0:3], v[174:177], v[206:209], v[0:3]
	s_barrier
	s_setprio 0
	s_add_i32 s82, s82, 2
	s_add_u32 s24, s24, 0x10000
	s_addc_u32 s25, s25, 0
	s_add_u32 s0, s0, 0x10000
	s_addc_u32 s1, s1, 0
